# RWKV scan consumer: all six LDS reads in one burst, S*w products in the p-chain gaps, interleaved chunk-tail reductions (combined)
# speedup vs baseline: 1.0026x; 1.0026x over previous
.LBB0_1750:
	s_and_b32 s23, s22, 1
	s_mul_i32 s2, s23, 0xc000
	s_add_i32 s2, s2, 0
	v_add_u32_e32 v20, s2, v10
	s_add_i32 s2, s2, s5
	v_lshl_add_u32 v21, v1, 2, s2
	ds_read_b128 v[36:39], v20 offset:0
	ds_read_b128 v[40:43], v20 offset:8192
	ds_read_b64 v[56:57], v21 offset:40960
	ds_read_b128 v[48:51], v20 offset:24576
	ds_read_b128 v[44:47], v20 offset:16384
	ds_read_b128 v[52:55], v20 offset:32768
	s_waitcnt lgkmcnt(0)
	ds_read_b128 v[60:63], v20 offset:256
	ds_read_b128 v[64:67], v20 offset:8448
	ds_read_b64 v[80:81], v21 offset:41216
	ds_read_b128 v[72:75], v20 offset:24832
	ds_read_b128 v[68:71], v20 offset:16640
	ds_read_b128 v[76:79], v20 offset:33024
	v_pk_mul_f32 v[22:23], v[2:3], v[36:37] op_sel:[0,0] op_sel_hi:[1,0]
	v_pk_mul_f32 v[84:85], v[2:3], v[40:41] op_sel:[0,0] op_sel_hi:[1,0]
	v_pk_fma_f32 v[22:23], v[4:5], v[36:37], v[22:23] op_sel:[0,1,0] op_sel_hi:[1,1,1]
	v_pk_mul_f32 v[86:87], v[4:5], v[40:41] op_sel:[0,1] op_sel_hi:[1,1]
	v_pk_fma_f32 v[22:23], v[6:7], v[38:39], v[22:23] op_sel:[0,0,0] op_sel_hi:[1,0,1]
	v_pk_mul_f32 v[88:89], v[6:7], v[42:43] op_sel:[0,0] op_sel_hi:[1,0]
	v_pk_fma_f32 v[22:23], v[8:9], v[38:39], v[22:23] op_sel:[0,1,0] op_sel_hi:[1,1,1]
	v_pk_mul_f32 v[90:91], v[8:9], v[42:43] op_sel:[0,1] op_sel_hi:[1,1]
	s_nop 0
	v_add_f32_dpp v22, v22, v22 quad_perm:[1,0,3,2] row_mask:0xf bank_mask:0xf
	v_add_f32_dpp v23, v23, v23 quad_perm:[1,0,3,2] row_mask:0xf bank_mask:0xf
	v_pk_fma_f32 v[84:85], v[48:49], v[56:57], v[84:85] op_sel:[0,0,0] op_sel_hi:[0,1,1]
	v_add_f32_dpp v22, v22, v22 quad_perm:[2,3,0,1] row_mask:0xf bank_mask:0xf
	v_add_f32_dpp v23, v23, v23 quad_perm:[2,3,0,1] row_mask:0xf bank_mask:0xf
	v_pk_fma_f32 v[86:87], v[48:49], v[56:57], v[86:87] op_sel:[1,0,0] op_sel_hi:[1,1,1]
	v_add_f32_dpp v22, v22, v22 row_half_mirror row_mask:0xf bank_mask:0xf
	v_add_f32_dpp v23, v23, v23 row_half_mirror row_mask:0xf bank_mask:0xf
	v_pk_fma_f32 v[88:89], v[50:51], v[56:57], v[88:89] op_sel:[0,0,0] op_sel_hi:[0,1,1]
	v_add_f32_dpp v22, v22, v22 row_mirror row_mask:0xf bank_mask:0xf
	v_add_f32_dpp v23, v23, v23 row_mirror row_mask:0xf bank_mask:0xf
	v_pk_fma_f32 v[90:91], v[50:51], v[56:57], v[90:91] op_sel:[1,0,0] op_sel_hi:[1,1,1]
	v_pk_fma_f32 v[2:3], v[44:45], v[22:23], v[84:85] op_sel:[0,0,0] op_sel_hi:[0,1,1] neg_lo:[1,0,0] neg_hi:[1,0,0]
	v_pk_fma_f32 v[4:5], v[44:45], v[22:23], v[86:87] op_sel:[1,0,0] op_sel_hi:[1,1,1] neg_lo:[1,0,0] neg_hi:[1,0,0]
	v_pk_fma_f32 v[6:7], v[46:47], v[22:23], v[88:89] op_sel:[0,0,0] op_sel_hi:[0,1,1] neg_lo:[1,0,0] neg_hi:[1,0,0]
	v_pk_fma_f32 v[8:9], v[46:47], v[22:23], v[90:91] op_sel:[1,0,0] op_sel_hi:[1,1,1] neg_lo:[1,0,0] neg_hi:[1,0,0]
	s_waitcnt lgkmcnt(0)
	ds_read_b128 v[36:39], v20 offset:512
	ds_read_b128 v[40:43], v20 offset:8704
	ds_read_b64 v[56:57], v21 offset:41472
	ds_read_b128 v[48:51], v20 offset:25088
	ds_read_b128 v[44:47], v20 offset:16896
	ds_read_b128 v[92:95], v20 offset:33280
	v_pk_mul_f32 v[22:23], v[2:3], v[60:61] op_sel:[0,0] op_sel_hi:[1,0]
	v_pk_mul_f32 v[24:25], v[2:3], v[52:53] op_sel:[0,0] op_sel_hi:[1,0]
	v_pk_mul_f32 v[84:85], v[2:3], v[64:65] op_sel:[0,0] op_sel_hi:[1,0]
	v_pk_fma_f32 v[22:23], v[4:5], v[60:61], v[22:23] op_sel:[0,1,0] op_sel_hi:[1,1,1]
	v_pk_fma_f32 v[24:25], v[4:5], v[52:53], v[24:25] op_sel:[0,1,0] op_sel_hi:[1,1,1]
	v_pk_mul_f32 v[86:87], v[4:5], v[64:65] op_sel:[0,1] op_sel_hi:[1,1]
	v_pk_fma_f32 v[22:23], v[6:7], v[62:63], v[22:23] op_sel:[0,0,0] op_sel_hi:[1,0,1]
	v_pk_fma_f32 v[24:25], v[6:7], v[54:55], v[24:25] op_sel:[0,0,0] op_sel_hi:[1,0,1]
	v_pk_mul_f32 v[88:89], v[6:7], v[66:67] op_sel:[0,0] op_sel_hi:[1,0]
	v_pk_fma_f32 v[22:23], v[8:9], v[62:63], v[22:23] op_sel:[0,1,0] op_sel_hi:[1,1,1]
	v_pk_fma_f32 v[24:25], v[8:9], v[54:55], v[24:25] op_sel:[0,1,0] op_sel_hi:[1,1,1]
	v_pk_mul_f32 v[90:91], v[8:9], v[66:67] op_sel:[0,1] op_sel_hi:[1,1]
	v_add_f32_dpp v22, v22, v22 quad_perm:[1,0,3,2] row_mask:0xf bank_mask:0xf
	v_add_f32_dpp v23, v23, v23 quad_perm:[1,0,3,2] row_mask:0xf bank_mask:0xf
	v_pk_fma_f32 v[84:85], v[72:73], v[80:81], v[84:85] op_sel:[0,0,0] op_sel_hi:[0,1,1]
	v_add_f32_dpp v22, v22, v22 quad_perm:[2,3,0,1] row_mask:0xf bank_mask:0xf
	v_add_f32_dpp v23, v23, v23 quad_perm:[2,3,0,1] row_mask:0xf bank_mask:0xf
	v_pk_fma_f32 v[86:87], v[72:73], v[80:81], v[86:87] op_sel:[1,0,0] op_sel_hi:[1,1,1]
	v_add_f32_dpp v22, v22, v22 row_half_mirror row_mask:0xf bank_mask:0xf
	v_add_f32_dpp v23, v23, v23 row_half_mirror row_mask:0xf bank_mask:0xf
	v_pk_fma_f32 v[88:89], v[74:75], v[80:81], v[88:89] op_sel:[0,0,0] op_sel_hi:[0,1,1]
	v_add_f32_dpp v22, v22, v22 row_mirror row_mask:0xf bank_mask:0xf
	v_add_f32_dpp v23, v23, v23 row_mirror row_mask:0xf bank_mask:0xf
	v_pk_fma_f32 v[90:91], v[74:75], v[80:81], v[90:91] op_sel:[1,0,0] op_sel_hi:[1,1,1]
	v_pk_fma_f32 v[2:3], v[68:69], v[22:23], v[84:85] op_sel:[0,0,0] op_sel_hi:[0,1,1] neg_lo:[1,0,0] neg_hi:[1,0,0]
	v_pk_fma_f32 v[4:5], v[68:69], v[22:23], v[86:87] op_sel:[1,0,0] op_sel_hi:[1,1,1] neg_lo:[1,0,0] neg_hi:[1,0,0]
	v_pk_fma_f32 v[6:7], v[70:71], v[22:23], v[88:89] op_sel:[0,0,0] op_sel_hi:[0,1,1] neg_lo:[1,0,0] neg_hi:[1,0,0]
	v_pk_fma_f32 v[8:9], v[70:71], v[22:23], v[90:91] op_sel:[1,0,0] op_sel_hi:[1,1,1] neg_lo:[1,0,0] neg_hi:[1,0,0]
	s_waitcnt lgkmcnt(0)
	ds_read_b128 v[60:63], v20 offset:768
	ds_read_b128 v[64:67], v20 offset:8960
	ds_read_b64 v[80:81], v21 offset:41728
	ds_read_b128 v[72:75], v20 offset:25344
	ds_read_b128 v[68:71], v20 offset:17152
	ds_read_b128 v[52:55], v20 offset:33536
	v_pk_mul_f32 v[22:23], v[2:3], v[36:37] op_sel:[0,0] op_sel_hi:[1,0]
	v_pk_mul_f32 v[26:27], v[2:3], v[76:77] op_sel:[0,0] op_sel_hi:[1,0]
	v_pk_mul_f32 v[84:85], v[2:3], v[40:41] op_sel:[0,0] op_sel_hi:[1,0]
	v_pk_fma_f32 v[22:23], v[4:5], v[36:37], v[22:23] op_sel:[0,1,0] op_sel_hi:[1,1,1]
	v_pk_fma_f32 v[26:27], v[4:5], v[76:77], v[26:27] op_sel:[0,1,0] op_sel_hi:[1,1,1]
	v_pk_mul_f32 v[86:87], v[4:5], v[40:41] op_sel:[0,1] op_sel_hi:[1,1]
	v_pk_fma_f32 v[22:23], v[6:7], v[38:39], v[22:23] op_sel:[0,0,0] op_sel_hi:[1,0,1]
	v_pk_fma_f32 v[26:27], v[6:7], v[78:79], v[26:27] op_sel:[0,0,0] op_sel_hi:[1,0,1]
	v_pk_mul_f32 v[88:89], v[6:7], v[42:43] op_sel:[0,0] op_sel_hi:[1,0]
	v_pk_fma_f32 v[22:23], v[8:9], v[38:39], v[22:23] op_sel:[0,1,0] op_sel_hi:[1,1,1]
	v_pk_fma_f32 v[26:27], v[8:9], v[78:79], v[26:27] op_sel:[0,1,0] op_sel_hi:[1,1,1]
	v_pk_mul_f32 v[90:91], v[8:9], v[42:43] op_sel:[0,1] op_sel_hi:[1,1]
	v_add_f32_dpp v22, v22, v22 quad_perm:[1,0,3,2] row_mask:0xf bank_mask:0xf
	v_add_f32_dpp v23, v23, v23 quad_perm:[1,0,3,2] row_mask:0xf bank_mask:0xf
	v_pk_fma_f32 v[84:85], v[48:49], v[56:57], v[84:85] op_sel:[0,0,0] op_sel_hi:[0,1,1]
	v_add_f32_dpp v22, v22, v22 quad_perm:[2,3,0,1] row_mask:0xf bank_mask:0xf
	v_add_f32_dpp v23, v23, v23 quad_perm:[2,3,0,1] row_mask:0xf bank_mask:0xf
	v_pk_fma_f32 v[86:87], v[48:49], v[56:57], v[86:87] op_sel:[1,0,0] op_sel_hi:[1,1,1]
	v_add_f32_dpp v22, v22, v22 row_half_mirror row_mask:0xf bank_mask:0xf
	v_add_f32_dpp v23, v23, v23 row_half_mirror row_mask:0xf bank_mask:0xf
	v_pk_fma_f32 v[88:89], v[50:51], v[56:57], v[88:89] op_sel:[0,0,0] op_sel_hi:[0,1,1]
	v_add_f32_dpp v22, v22, v22 row_mirror row_mask:0xf bank_mask:0xf
	v_add_f32_dpp v23, v23, v23 row_mirror row_mask:0xf bank_mask:0xf
	v_pk_fma_f32 v[90:91], v[50:51], v[56:57], v[90:91] op_sel:[1,0,0] op_sel_hi:[1,1,1]
	v_pk_fma_f32 v[2:3], v[44:45], v[22:23], v[84:85] op_sel:[0,0,0] op_sel_hi:[0,1,1] neg_lo:[1,0,0] neg_hi:[1,0,0]
	v_pk_fma_f32 v[4:5], v[44:45], v[22:23], v[86:87] op_sel:[1,0,0] op_sel_hi:[1,1,1] neg_lo:[1,0,0] neg_hi:[1,0,0]
	v_pk_fma_f32 v[6:7], v[46:47], v[22:23], v[88:89] op_sel:[0,0,0] op_sel_hi:[0,1,1] neg_lo:[1,0,0] neg_hi:[1,0,0]
	v_pk_fma_f32 v[8:9], v[46:47], v[22:23], v[90:91] op_sel:[1,0,0] op_sel_hi:[1,1,1] neg_lo:[1,0,0] neg_hi:[1,0,0]
	s_waitcnt lgkmcnt(0)
	ds_read_b128 v[36:39], v20 offset:1024
	ds_read_b128 v[40:43], v20 offset:9216
	ds_read_b64 v[56:57], v21 offset:41984
	ds_read_b128 v[48:51], v20 offset:25600
	ds_read_b128 v[44:47], v20 offset:17408
	ds_read_b128 v[76:79], v20 offset:33792
	v_pk_mul_f32 v[22:23], v[2:3], v[60:61] op_sel:[0,0] op_sel_hi:[1,0]
	v_pk_mul_f32 v[28:29], v[2:3], v[92:93] op_sel:[0,0] op_sel_hi:[1,0]
	v_pk_mul_f32 v[84:85], v[2:3], v[64:65] op_sel:[0,0] op_sel_hi:[1,0]
	v_pk_fma_f32 v[22:23], v[4:5], v[60:61], v[22:23] op_sel:[0,1,0] op_sel_hi:[1,1,1]
	v_pk_fma_f32 v[28:29], v[4:5], v[92:93], v[28:29] op_sel:[0,1,0] op_sel_hi:[1,1,1]
	v_pk_mul_f32 v[86:87], v[4:5], v[64:65] op_sel:[0,1] op_sel_hi:[1,1]
	v_pk_fma_f32 v[22:23], v[6:7], v[62:63], v[22:23] op_sel:[0,0,0] op_sel_hi:[1,0,1]
	v_pk_fma_f32 v[28:29], v[6:7], v[94:95], v[28:29] op_sel:[0,0,0] op_sel_hi:[1,0,1]
	v_pk_mul_f32 v[88:89], v[6:7], v[66:67] op_sel:[0,0] op_sel_hi:[1,0]
	v_pk_fma_f32 v[22:23], v[8:9], v[62:63], v[22:23] op_sel:[0,1,0] op_sel_hi:[1,1,1]
	v_pk_fma_f32 v[28:29], v[8:9], v[94:95], v[28:29] op_sel:[0,1,0] op_sel_hi:[1,1,1]
	v_pk_mul_f32 v[90:91], v[8:9], v[66:67] op_sel:[0,1] op_sel_hi:[1,1]
	v_add_f32_dpp v24, v24, v24 row_ror:12 row_mask:0xf bank_mask:0x5
	v_add_f32_dpp v25, v25, v25 row_ror:4 row_mask:0xf bank_mask:0xa
	v_add_f32_dpp v22, v22, v22 quad_perm:[1,0,3,2] row_mask:0xf bank_mask:0xf
	v_add_f32_dpp v23, v23, v23 quad_perm:[1,0,3,2] row_mask:0xf bank_mask:0xf
	v_pk_fma_f32 v[84:85], v[72:73], v[80:81], v[84:85] op_sel:[0,0,0] op_sel_hi:[0,1,1]
	v_add_f32_dpp v26, v26, v26 row_ror:12 row_mask:0xf bank_mask:0x5
	v_add_f32_dpp v22, v22, v22 quad_perm:[2,3,0,1] row_mask:0xf bank_mask:0xf
	v_add_f32_dpp v23, v23, v23 quad_perm:[2,3,0,1] row_mask:0xf bank_mask:0xf
	v_pk_fma_f32 v[86:87], v[72:73], v[80:81], v[86:87] op_sel:[1,0,0] op_sel_hi:[1,1,1]
	v_add_f32_dpp v27, v27, v27 row_ror:4 row_mask:0xf bank_mask:0xa
	v_add_f32_dpp v22, v22, v22 row_half_mirror row_mask:0xf bank_mask:0xf
	v_add_f32_dpp v23, v23, v23 row_half_mirror row_mask:0xf bank_mask:0xf
	v_pk_fma_f32 v[88:89], v[74:75], v[80:81], v[88:89] op_sel:[0,0,0] op_sel_hi:[0,1,1]
	v_mov_b32_dpp v24, v25 quad_perm:[0,1,2,3] row_mask:0xf bank_mask:0xa
	v_add_f32_dpp v22, v22, v22 row_mirror row_mask:0xf bank_mask:0xf
	v_add_f32_dpp v23, v23, v23 row_mirror row_mask:0xf bank_mask:0xf
	v_pk_fma_f32 v[90:91], v[74:75], v[80:81], v[90:91] op_sel:[1,0,0] op_sel_hi:[1,1,1]
	v_mov_b32_dpp v26, v27 quad_perm:[0,1,2,3] row_mask:0xf bank_mask:0xa
	v_pk_fma_f32 v[2:3], v[68:69], v[22:23], v[84:85] op_sel:[0,0,0] op_sel_hi:[0,1,1] neg_lo:[1,0,0] neg_hi:[1,0,0]
	v_pk_fma_f32 v[4:5], v[68:69], v[22:23], v[86:87] op_sel:[1,0,0] op_sel_hi:[1,1,1] neg_lo:[1,0,0] neg_hi:[1,0,0]
	v_pk_fma_f32 v[6:7], v[70:71], v[22:23], v[88:89] op_sel:[0,0,0] op_sel_hi:[0,1,1] neg_lo:[1,0,0] neg_hi:[1,0,0]
	v_pk_fma_f32 v[8:9], v[70:71], v[22:23], v[90:91] op_sel:[1,0,0] op_sel_hi:[1,1,1] neg_lo:[1,0,0] neg_hi:[1,0,0]
	s_waitcnt lgkmcnt(0)
	ds_read_b128 v[60:63], v20 offset:1280
	ds_read_b128 v[64:67], v20 offset:9472
	ds_read_b64 v[80:81], v21 offset:42240
	ds_read_b128 v[72:75], v20 offset:25856
	ds_read_b128 v[68:71], v20 offset:17664
	ds_read_b128 v[92:95], v20 offset:34048
	v_pk_mul_f32 v[22:23], v[2:3], v[36:37] op_sel:[0,0] op_sel_hi:[1,0]
	v_pk_mul_f32 v[58:59], v[2:3], v[52:53] op_sel:[0,0] op_sel_hi:[1,0]
	v_pk_mul_f32 v[84:85], v[2:3], v[40:41] op_sel:[0,0] op_sel_hi:[1,0]
	v_pk_fma_f32 v[22:23], v[4:5], v[36:37], v[22:23] op_sel:[0,1,0] op_sel_hi:[1,1,1]
	v_pk_fma_f32 v[58:59], v[4:5], v[52:53], v[58:59] op_sel:[0,1,0] op_sel_hi:[1,1,1]
	v_pk_mul_f32 v[86:87], v[4:5], v[40:41] op_sel:[0,1] op_sel_hi:[1,1]
	v_pk_fma_f32 v[22:23], v[6:7], v[38:39], v[22:23] op_sel:[0,0,0] op_sel_hi:[1,0,1]
	v_pk_fma_f32 v[58:59], v[6:7], v[54:55], v[58:59] op_sel:[0,0,0] op_sel_hi:[1,0,1]
	v_pk_mul_f32 v[88:89], v[6:7], v[42:43] op_sel:[0,0] op_sel_hi:[1,0]
	v_pk_fma_f32 v[22:23], v[8:9], v[38:39], v[22:23] op_sel:[0,1,0] op_sel_hi:[1,1,1]
	v_pk_fma_f32 v[58:59], v[8:9], v[54:55], v[58:59] op_sel:[0,1,0] op_sel_hi:[1,1,1]
	v_pk_mul_f32 v[90:91], v[8:9], v[42:43] op_sel:[0,1] op_sel_hi:[1,1]
	v_add_f32_dpp v24, v24, v24 row_ror:8 row_mask:0xf bank_mask:0x3
	v_add_f32_dpp v26, v26, v26 row_ror:8 row_mask:0xf bank_mask:0xc
	v_add_f32_dpp v22, v22, v22 quad_perm:[1,0,3,2] row_mask:0xf bank_mask:0xf
	v_add_f32_dpp v23, v23, v23 quad_perm:[1,0,3,2] row_mask:0xf bank_mask:0xf
	v_pk_fma_f32 v[84:85], v[48:49], v[56:57], v[84:85] op_sel:[0,0,0] op_sel_hi:[0,1,1]
	v_mov_b32_dpp v24, v26 quad_perm:[0,1,2,3] row_mask:0xf bank_mask:0xc
	v_add_f32_dpp v22, v22, v22 quad_perm:[2,3,0,1] row_mask:0xf bank_mask:0xf
	v_add_f32_dpp v23, v23, v23 quad_perm:[2,3,0,1] row_mask:0xf bank_mask:0xf
	v_pk_fma_f32 v[86:87], v[48:49], v[56:57], v[86:87] op_sel:[1,0,0] op_sel_hi:[1,1,1]
	v_add_f32_dpp v24, v24, v24 quad_perm:[1,0,3,2] row_mask:0xf bank_mask:0xf
	v_add_f32_dpp v22, v22, v22 row_half_mirror row_mask:0xf bank_mask:0xf
	v_add_f32_dpp v23, v23, v23 row_half_mirror row_mask:0xf bank_mask:0xf
	v_pk_fma_f32 v[88:89], v[50:51], v[56:57], v[88:89] op_sel:[0,0,0] op_sel_hi:[0,1,1]
	v_add_f32_dpp v24, v24, v24 quad_perm:[2,3,0,1] row_mask:0xf bank_mask:0xf
	v_add_f32_dpp v22, v22, v22 row_mirror row_mask:0xf bank_mask:0xf
	v_add_f32_dpp v23, v23, v23 row_mirror row_mask:0xf bank_mask:0xf
	v_pk_fma_f32 v[90:91], v[50:51], v[56:57], v[90:91] op_sel:[1,0,0] op_sel_hi:[1,1,1]
	v_cndmask_b32_e64 v30, 0, v24, s[0:1]
	v_pk_fma_f32 v[2:3], v[44:45], v[22:23], v[84:85] op_sel:[0,0,0] op_sel_hi:[0,1,1] neg_lo:[1,0,0] neg_hi:[1,0,0]
	v_pk_fma_f32 v[4:5], v[44:45], v[22:23], v[86:87] op_sel:[1,0,0] op_sel_hi:[1,1,1] neg_lo:[1,0,0] neg_hi:[1,0,0]
	v_pk_fma_f32 v[6:7], v[46:47], v[22:23], v[88:89] op_sel:[0,0,0] op_sel_hi:[0,1,1] neg_lo:[1,0,0] neg_hi:[1,0,0]
	v_pk_fma_f32 v[8:9], v[46:47], v[22:23], v[90:91] op_sel:[1,0,0] op_sel_hi:[1,1,1] neg_lo:[1,0,0] neg_hi:[1,0,0]
	s_waitcnt lgkmcnt(0)
	ds_read_b128 v[36:39], v20 offset:1536
	ds_read_b128 v[40:43], v20 offset:9728
	ds_read_b64 v[56:57], v21 offset:42496
	ds_read_b128 v[48:51], v20 offset:26112
	ds_read_b128 v[44:47], v20 offset:17920
	ds_read_b128 v[52:55], v20 offset:34304
	v_pk_mul_f32 v[22:23], v[2:3], v[60:61] op_sel:[0,0] op_sel_hi:[1,0]
	v_pk_mul_f32 v[24:25], v[2:3], v[76:77] op_sel:[0,0] op_sel_hi:[1,0]
	v_pk_mul_f32 v[84:85], v[2:3], v[64:65] op_sel:[0,0] op_sel_hi:[1,0]
	v_pk_fma_f32 v[22:23], v[4:5], v[60:61], v[22:23] op_sel:[0,1,0] op_sel_hi:[1,1,1]
	v_pk_fma_f32 v[24:25], v[4:5], v[76:77], v[24:25] op_sel:[0,1,0] op_sel_hi:[1,1,1]
	v_pk_mul_f32 v[86:87], v[4:5], v[64:65] op_sel:[0,1] op_sel_hi:[1,1]
	v_pk_fma_f32 v[22:23], v[6:7], v[62:63], v[22:23] op_sel:[0,0,0] op_sel_hi:[1,0,1]
	v_pk_fma_f32 v[24:25], v[6:7], v[78:79], v[24:25] op_sel:[0,0,0] op_sel_hi:[1,0,1]
	v_pk_mul_f32 v[88:89], v[6:7], v[66:67] op_sel:[0,0] op_sel_hi:[1,0]
	v_pk_fma_f32 v[22:23], v[8:9], v[62:63], v[22:23] op_sel:[0,1,0] op_sel_hi:[1,1,1]
	v_pk_fma_f32 v[24:25], v[8:9], v[78:79], v[24:25] op_sel:[0,1,0] op_sel_hi:[1,1,1]
	v_pk_mul_f32 v[90:91], v[8:9], v[66:67] op_sel:[0,1] op_sel_hi:[1,1]
	v_add_f32_dpp v28, v28, v28 row_ror:12 row_mask:0xf bank_mask:0x5
	v_add_f32_dpp v29, v29, v29 row_ror:4 row_mask:0xf bank_mask:0xa
	v_add_f32_dpp v22, v22, v22 quad_perm:[1,0,3,2] row_mask:0xf bank_mask:0xf
	v_add_f32_dpp v23, v23, v23 quad_perm:[1,0,3,2] row_mask:0xf bank_mask:0xf
	v_pk_fma_f32 v[84:85], v[72:73], v[80:81], v[84:85] op_sel:[0,0,0] op_sel_hi:[0,1,1]
	v_add_f32_dpp v58, v58, v58 row_ror:12 row_mask:0xf bank_mask:0x5
	v_add_f32_dpp v22, v22, v22 quad_perm:[2,3,0,1] row_mask:0xf bank_mask:0xf
	v_add_f32_dpp v23, v23, v23 quad_perm:[2,3,0,1] row_mask:0xf bank_mask:0xf
	v_pk_fma_f32 v[86:87], v[72:73], v[80:81], v[86:87] op_sel:[1,0,0] op_sel_hi:[1,1,1]
	v_add_f32_dpp v59, v59, v59 row_ror:4 row_mask:0xf bank_mask:0xa
	v_add_f32_dpp v22, v22, v22 row_half_mirror row_mask:0xf bank_mask:0xf
	v_add_f32_dpp v23, v23, v23 row_half_mirror row_mask:0xf bank_mask:0xf
	v_pk_fma_f32 v[88:89], v[74:75], v[80:81], v[88:89] op_sel:[0,0,0] op_sel_hi:[0,1,1]
	v_mov_b32_dpp v28, v29 quad_perm:[0,1,2,3] row_mask:0xf bank_mask:0xa
	v_add_f32_dpp v22, v22, v22 row_mirror row_mask:0xf bank_mask:0xf
	v_add_f32_dpp v23, v23, v23 row_mirror row_mask:0xf bank_mask:0xf
	v_pk_fma_f32 v[90:91], v[74:75], v[80:81], v[90:91] op_sel:[1,0,0] op_sel_hi:[1,1,1]
	v_mov_b32_dpp v58, v59 quad_perm:[0,1,2,3] row_mask:0xf bank_mask:0xa
	v_pk_fma_f32 v[2:3], v[68:69], v[22:23], v[84:85] op_sel:[0,0,0] op_sel_hi:[0,1,1] neg_lo:[1,0,0] neg_hi:[1,0,0]
	v_pk_fma_f32 v[4:5], v[68:69], v[22:23], v[86:87] op_sel:[1,0,0] op_sel_hi:[1,1,1] neg_lo:[1,0,0] neg_hi:[1,0,0]
	v_pk_fma_f32 v[6:7], v[70:71], v[22:23], v[88:89] op_sel:[0,0,0] op_sel_hi:[0,1,1] neg_lo:[1,0,0] neg_hi:[1,0,0]
	v_pk_fma_f32 v[8:9], v[70:71], v[22:23], v[90:91] op_sel:[1,0,0] op_sel_hi:[1,1,1] neg_lo:[1,0,0] neg_hi:[1,0,0]
	s_waitcnt lgkmcnt(0)
	ds_read_b128 v[60:63], v20 offset:1792
	ds_read_b128 v[64:67], v20 offset:9984
	ds_read_b64 v[80:81], v21 offset:42752
	ds_read_b128 v[72:75], v20 offset:26368
	ds_read_b128 v[68:71], v20 offset:18176
	ds_read_b128 v[76:79], v20 offset:34560
	v_pk_mul_f32 v[22:23], v[2:3], v[36:37] op_sel:[0,0] op_sel_hi:[1,0]
	v_pk_mul_f32 v[26:27], v[2:3], v[92:93] op_sel:[0,0] op_sel_hi:[1,0]
	v_pk_mul_f32 v[84:85], v[2:3], v[40:41] op_sel:[0,0] op_sel_hi:[1,0]
	v_pk_fma_f32 v[22:23], v[4:5], v[36:37], v[22:23] op_sel:[0,1,0] op_sel_hi:[1,1,1]
	v_pk_fma_f32 v[26:27], v[4:5], v[92:93], v[26:27] op_sel:[0,1,0] op_sel_hi:[1,1,1]
	v_pk_mul_f32 v[86:87], v[4:5], v[40:41] op_sel:[0,1] op_sel_hi:[1,1]
	v_pk_fma_f32 v[22:23], v[6:7], v[38:39], v[22:23] op_sel:[0,0,0] op_sel_hi:[1,0,1]
	v_pk_fma_f32 v[26:27], v[6:7], v[94:95], v[26:27] op_sel:[0,0,0] op_sel_hi:[1,0,1]
	v_pk_mul_f32 v[88:89], v[6:7], v[42:43] op_sel:[0,0] op_sel_hi:[1,0]
	v_pk_fma_f32 v[22:23], v[8:9], v[38:39], v[22:23] op_sel:[0,1,0] op_sel_hi:[1,1,1]
	v_pk_fma_f32 v[26:27], v[8:9], v[94:95], v[26:27] op_sel:[0,1,0] op_sel_hi:[1,1,1]
	v_pk_mul_f32 v[90:91], v[8:9], v[42:43] op_sel:[0,1] op_sel_hi:[1,1]
	v_add_f32_dpp v28, v28, v28 row_ror:8 row_mask:0xf bank_mask:0x3
	v_add_f32_dpp v58, v58, v58 row_ror:8 row_mask:0xf bank_mask:0xc
	v_add_f32_dpp v22, v22, v22 quad_perm:[1,0,3,2] row_mask:0xf bank_mask:0xf
	v_add_f32_dpp v23, v23, v23 quad_perm:[1,0,3,2] row_mask:0xf bank_mask:0xf
	v_pk_fma_f32 v[84:85], v[48:49], v[56:57], v[84:85] op_sel:[0,0,0] op_sel_hi:[0,1,1]
	v_mov_b32_dpp v28, v58 quad_perm:[0,1,2,3] row_mask:0xf bank_mask:0xc
	v_add_f32_dpp v22, v22, v22 quad_perm:[2,3,0,1] row_mask:0xf bank_mask:0xf
	v_add_f32_dpp v23, v23, v23 quad_perm:[2,3,0,1] row_mask:0xf bank_mask:0xf
	v_pk_fma_f32 v[86:87], v[48:49], v[56:57], v[86:87] op_sel:[1,0,0] op_sel_hi:[1,1,1]
	v_add_f32_dpp v28, v28, v28 quad_perm:[1,0,3,2] row_mask:0xf bank_mask:0xf
	v_add_f32_dpp v22, v22, v22 row_half_mirror row_mask:0xf bank_mask:0xf
	v_add_f32_dpp v23, v23, v23 row_half_mirror row_mask:0xf bank_mask:0xf
	v_pk_fma_f32 v[88:89], v[50:51], v[56:57], v[88:89] op_sel:[0,0,0] op_sel_hi:[0,1,1]
	v_add_f32_dpp v28, v28, v28 quad_perm:[2,3,0,1] row_mask:0xf bank_mask:0xf
	v_add_f32_dpp v22, v22, v22 row_mirror row_mask:0xf bank_mask:0xf
	v_add_f32_dpp v23, v23, v23 row_mirror row_mask:0xf bank_mask:0xf
	v_pk_fma_f32 v[90:91], v[50:51], v[56:57], v[90:91] op_sel:[1,0,0] op_sel_hi:[1,1,1]
	v_cndmask_b32_e64 v30, v30, v28, s[6:7]
	v_pk_fma_f32 v[2:3], v[44:45], v[22:23], v[84:85] op_sel:[0,0,0] op_sel_hi:[0,1,1] neg_lo:[1,0,0] neg_hi:[1,0,0]
	v_pk_fma_f32 v[4:5], v[44:45], v[22:23], v[86:87] op_sel:[1,0,0] op_sel_hi:[1,1,1] neg_lo:[1,0,0] neg_hi:[1,0,0]
	v_pk_fma_f32 v[6:7], v[46:47], v[22:23], v[88:89] op_sel:[0,0,0] op_sel_hi:[0,1,1] neg_lo:[1,0,0] neg_hi:[1,0,0]
	v_pk_fma_f32 v[8:9], v[46:47], v[22:23], v[90:91] op_sel:[1,0,0] op_sel_hi:[1,1,1] neg_lo:[1,0,0] neg_hi:[1,0,0]
	s_waitcnt lgkmcnt(0)
	ds_read_b128 v[36:39], v20 offset:2048
	ds_read_b128 v[40:43], v20 offset:10240
	ds_read_b64 v[56:57], v21 offset:43008
	ds_read_b128 v[48:51], v20 offset:26624
	ds_read_b128 v[44:47], v20 offset:18432
	ds_read_b128 v[92:95], v20 offset:34816
	v_pk_mul_f32 v[22:23], v[2:3], v[60:61] op_sel:[0,0] op_sel_hi:[1,0]
	v_pk_mul_f32 v[28:29], v[2:3], v[52:53] op_sel:[0,0] op_sel_hi:[1,0]
	v_pk_mul_f32 v[84:85], v[2:3], v[64:65] op_sel:[0,0] op_sel_hi:[1,0]
	v_pk_fma_f32 v[22:23], v[4:5], v[60:61], v[22:23] op_sel:[0,1,0] op_sel_hi:[1,1,1]
	v_pk_fma_f32 v[28:29], v[4:5], v[52:53], v[28:29] op_sel:[0,1,0] op_sel_hi:[1,1,1]
	v_pk_mul_f32 v[86:87], v[4:5], v[64:65] op_sel:[0,1] op_sel_hi:[1,1]
	v_pk_fma_f32 v[22:23], v[6:7], v[62:63], v[22:23] op_sel:[0,0,0] op_sel_hi:[1,0,1]
	v_pk_fma_f32 v[28:29], v[6:7], v[54:55], v[28:29] op_sel:[0,0,0] op_sel_hi:[1,0,1]
	v_pk_mul_f32 v[88:89], v[6:7], v[66:67] op_sel:[0,0] op_sel_hi:[1,0]
	v_pk_fma_f32 v[22:23], v[8:9], v[62:63], v[22:23] op_sel:[0,1,0] op_sel_hi:[1,1,1]
	v_pk_fma_f32 v[28:29], v[8:9], v[54:55], v[28:29] op_sel:[0,1,0] op_sel_hi:[1,1,1]
	v_pk_mul_f32 v[90:91], v[8:9], v[66:67] op_sel:[0,1] op_sel_hi:[1,1]
	v_add_f32_dpp v24, v24, v24 row_ror:12 row_mask:0xf bank_mask:0x5
	v_add_f32_dpp v25, v25, v25 row_ror:4 row_mask:0xf bank_mask:0xa
	v_add_f32_dpp v22, v22, v22 quad_perm:[1,0,3,2] row_mask:0xf bank_mask:0xf
	v_add_f32_dpp v23, v23, v23 quad_perm:[1,0,3,2] row_mask:0xf bank_mask:0xf
	v_pk_fma_f32 v[84:85], v[72:73], v[80:81], v[84:85] op_sel:[0,0,0] op_sel_hi:[0,1,1]
	v_add_f32_dpp v26, v26, v26 row_ror:12 row_mask:0xf bank_mask:0x5
	v_add_f32_dpp v22, v22, v22 quad_perm:[2,3,0,1] row_mask:0xf bank_mask:0xf
	v_add_f32_dpp v23, v23, v23 quad_perm:[2,3,0,1] row_mask:0xf bank_mask:0xf
	v_pk_fma_f32 v[86:87], v[72:73], v[80:81], v[86:87] op_sel:[1,0,0] op_sel_hi:[1,1,1]
	v_add_f32_dpp v27, v27, v27 row_ror:4 row_mask:0xf bank_mask:0xa
	v_add_f32_dpp v22, v22, v22 row_half_mirror row_mask:0xf bank_mask:0xf
	v_add_f32_dpp v23, v23, v23 row_half_mirror row_mask:0xf bank_mask:0xf
	v_pk_fma_f32 v[88:89], v[74:75], v[80:81], v[88:89] op_sel:[0,0,0] op_sel_hi:[0,1,1]
	v_mov_b32_dpp v24, v25 quad_perm:[0,1,2,3] row_mask:0xf bank_mask:0xa
	v_add_f32_dpp v22, v22, v22 row_mirror row_mask:0xf bank_mask:0xf
	v_add_f32_dpp v23, v23, v23 row_mirror row_mask:0xf bank_mask:0xf
	v_pk_fma_f32 v[90:91], v[74:75], v[80:81], v[90:91] op_sel:[1,0,0] op_sel_hi:[1,1,1]
	v_mov_b32_dpp v26, v27 quad_perm:[0,1,2,3] row_mask:0xf bank_mask:0xa
	v_pk_fma_f32 v[2:3], v[68:69], v[22:23], v[84:85] op_sel:[0,0,0] op_sel_hi:[0,1,1] neg_lo:[1,0,0] neg_hi:[1,0,0]
	v_pk_fma_f32 v[4:5], v[68:69], v[22:23], v[86:87] op_sel:[1,0,0] op_sel_hi:[1,1,1] neg_lo:[1,0,0] neg_hi:[1,0,0]
	v_pk_fma_f32 v[6:7], v[70:71], v[22:23], v[88:89] op_sel:[0,0,0] op_sel_hi:[0,1,1] neg_lo:[1,0,0] neg_hi:[1,0,0]
	v_pk_fma_f32 v[8:9], v[70:71], v[22:23], v[90:91] op_sel:[1,0,0] op_sel_hi:[1,1,1] neg_lo:[1,0,0] neg_hi:[1,0,0]
	s_waitcnt lgkmcnt(0)
	ds_read_b128 v[60:63], v20 offset:2304
	ds_read_b128 v[64:67], v20 offset:10496
	ds_read_b64 v[80:81], v21 offset:43264
	ds_read_b128 v[72:75], v20 offset:26880
	ds_read_b128 v[68:71], v20 offset:18688
	ds_read_b128 v[52:55], v20 offset:35072
	v_pk_mul_f32 v[22:23], v[2:3], v[36:37] op_sel:[0,0] op_sel_hi:[1,0]
	v_pk_mul_f32 v[58:59], v[2:3], v[76:77] op_sel:[0,0] op_sel_hi:[1,0]
	v_pk_mul_f32 v[84:85], v[2:3], v[40:41] op_sel:[0,0] op_sel_hi:[1,0]
	v_pk_fma_f32 v[22:23], v[4:5], v[36:37], v[22:23] op_sel:[0,1,0] op_sel_hi:[1,1,1]
	v_pk_fma_f32 v[58:59], v[4:5], v[76:77], v[58:59] op_sel:[0,1,0] op_sel_hi:[1,1,1]
	v_pk_mul_f32 v[86:87], v[4:5], v[40:41] op_sel:[0,1] op_sel_hi:[1,1]
	v_pk_fma_f32 v[22:23], v[6:7], v[38:39], v[22:23] op_sel:[0,0,0] op_sel_hi:[1,0,1]
	v_pk_fma_f32 v[58:59], v[6:7], v[78:79], v[58:59] op_sel:[0,0,0] op_sel_hi:[1,0,1]
	v_pk_mul_f32 v[88:89], v[6:7], v[42:43] op_sel:[0,0] op_sel_hi:[1,0]
	v_pk_fma_f32 v[22:23], v[8:9], v[38:39], v[22:23] op_sel:[0,1,0] op_sel_hi:[1,1,1]
	v_pk_fma_f32 v[58:59], v[8:9], v[78:79], v[58:59] op_sel:[0,1,0] op_sel_hi:[1,1,1]
	v_pk_mul_f32 v[90:91], v[8:9], v[42:43] op_sel:[0,1] op_sel_hi:[1,1]
	v_add_f32_dpp v24, v24, v24 row_ror:8 row_mask:0xf bank_mask:0x3
	v_add_f32_dpp v26, v26, v26 row_ror:8 row_mask:0xf bank_mask:0xc
	v_add_f32_dpp v22, v22, v22 quad_perm:[1,0,3,2] row_mask:0xf bank_mask:0xf
	v_add_f32_dpp v23, v23, v23 quad_perm:[1,0,3,2] row_mask:0xf bank_mask:0xf
	v_pk_fma_f32 v[84:85], v[48:49], v[56:57], v[84:85] op_sel:[0,0,0] op_sel_hi:[0,1,1]
	v_mov_b32_dpp v24, v26 quad_perm:[0,1,2,3] row_mask:0xf bank_mask:0xc
	v_add_f32_dpp v22, v22, v22 quad_perm:[2,3,0,1] row_mask:0xf bank_mask:0xf
	v_add_f32_dpp v23, v23, v23 quad_perm:[2,3,0,1] row_mask:0xf bank_mask:0xf
	v_pk_fma_f32 v[86:87], v[48:49], v[56:57], v[86:87] op_sel:[1,0,0] op_sel_hi:[1,1,1]
	v_add_f32_dpp v24, v24, v24 quad_perm:[1,0,3,2] row_mask:0xf bank_mask:0xf
	v_add_f32_dpp v22, v22, v22 row_half_mirror row_mask:0xf bank_mask:0xf
	v_add_f32_dpp v23, v23, v23 row_half_mirror row_mask:0xf bank_mask:0xf
	v_pk_fma_f32 v[88:89], v[50:51], v[56:57], v[88:89] op_sel:[0,0,0] op_sel_hi:[0,1,1]
	v_add_f32_dpp v24, v24, v24 quad_perm:[2,3,0,1] row_mask:0xf bank_mask:0xf
	v_add_f32_dpp v22, v22, v22 row_mirror row_mask:0xf bank_mask:0xf
	v_add_f32_dpp v23, v23, v23 row_mirror row_mask:0xf bank_mask:0xf
	v_pk_fma_f32 v[90:91], v[50:51], v[56:57], v[90:91] op_sel:[1,0,0] op_sel_hi:[1,1,1]
	v_cndmask_b32_e64 v30, v30, v24, s[8:9]
	v_pk_fma_f32 v[2:3], v[44:45], v[22:23], v[84:85] op_sel:[0,0,0] op_sel_hi:[0,1,1] neg_lo:[1,0,0] neg_hi:[1,0,0]
	v_pk_fma_f32 v[4:5], v[44:45], v[22:23], v[86:87] op_sel:[1,0,0] op_sel_hi:[1,1,1] neg_lo:[1,0,0] neg_hi:[1,0,0]
	v_pk_fma_f32 v[6:7], v[46:47], v[22:23], v[88:89] op_sel:[0,0,0] op_sel_hi:[0,1,1] neg_lo:[1,0,0] neg_hi:[1,0,0]
	v_pk_fma_f32 v[8:9], v[46:47], v[22:23], v[90:91] op_sel:[1,0,0] op_sel_hi:[1,1,1] neg_lo:[1,0,0] neg_hi:[1,0,0]
	s_waitcnt lgkmcnt(0)
	ds_read_b128 v[36:39], v20 offset:2560
	ds_read_b128 v[40:43], v20 offset:10752
	ds_read_b64 v[56:57], v21 offset:43520
	ds_read_b128 v[48:51], v20 offset:27136
	ds_read_b128 v[44:47], v20 offset:18944
	ds_read_b128 v[76:79], v20 offset:35328
	v_pk_mul_f32 v[22:23], v[2:3], v[60:61] op_sel:[0,0] op_sel_hi:[1,0]
	v_pk_mul_f32 v[24:25], v[2:3], v[92:93] op_sel:[0,0] op_sel_hi:[1,0]
	v_pk_mul_f32 v[84:85], v[2:3], v[64:65] op_sel:[0,0] op_sel_hi:[1,0]
	v_pk_fma_f32 v[22:23], v[4:5], v[60:61], v[22:23] op_sel:[0,1,0] op_sel_hi:[1,1,1]
	v_pk_fma_f32 v[24:25], v[4:5], v[92:93], v[24:25] op_sel:[0,1,0] op_sel_hi:[1,1,1]
	v_pk_mul_f32 v[86:87], v[4:5], v[64:65] op_sel:[0,1] op_sel_hi:[1,1]
	v_pk_fma_f32 v[22:23], v[6:7], v[62:63], v[22:23] op_sel:[0,0,0] op_sel_hi:[1,0,1]
	v_pk_fma_f32 v[24:25], v[6:7], v[94:95], v[24:25] op_sel:[0,0,0] op_sel_hi:[1,0,1]
	v_pk_mul_f32 v[88:89], v[6:7], v[66:67] op_sel:[0,0] op_sel_hi:[1,0]
	v_pk_fma_f32 v[22:23], v[8:9], v[62:63], v[22:23] op_sel:[0,1,0] op_sel_hi:[1,1,1]
	v_pk_fma_f32 v[24:25], v[8:9], v[94:95], v[24:25] op_sel:[0,1,0] op_sel_hi:[1,1,1]
	v_pk_mul_f32 v[90:91], v[8:9], v[66:67] op_sel:[0,1] op_sel_hi:[1,1]
	v_add_f32_dpp v28, v28, v28 row_ror:12 row_mask:0xf bank_mask:0x5
	v_add_f32_dpp v29, v29, v29 row_ror:4 row_mask:0xf bank_mask:0xa
	v_add_f32_dpp v22, v22, v22 quad_perm:[1,0,3,2] row_mask:0xf bank_mask:0xf
	v_add_f32_dpp v23, v23, v23 quad_perm:[1,0,3,2] row_mask:0xf bank_mask:0xf
	v_pk_fma_f32 v[84:85], v[72:73], v[80:81], v[84:85] op_sel:[0,0,0] op_sel_hi:[0,1,1]
	v_add_f32_dpp v58, v58, v58 row_ror:12 row_mask:0xf bank_mask:0x5
	v_add_f32_dpp v22, v22, v22 quad_perm:[2,3,0,1] row_mask:0xf bank_mask:0xf
	v_add_f32_dpp v23, v23, v23 quad_perm:[2,3,0,1] row_mask:0xf bank_mask:0xf
	v_pk_fma_f32 v[86:87], v[72:73], v[80:81], v[86:87] op_sel:[1,0,0] op_sel_hi:[1,1,1]
	v_add_f32_dpp v59, v59, v59 row_ror:4 row_mask:0xf bank_mask:0xa
	v_add_f32_dpp v22, v22, v22 row_half_mirror row_mask:0xf bank_mask:0xf
	v_add_f32_dpp v23, v23, v23 row_half_mirror row_mask:0xf bank_mask:0xf
	v_pk_fma_f32 v[88:89], v[74:75], v[80:81], v[88:89] op_sel:[0,0,0] op_sel_hi:[0,1,1]
	v_mov_b32_dpp v28, v29 quad_perm:[0,1,2,3] row_mask:0xf bank_mask:0xa
	v_add_f32_dpp v22, v22, v22 row_mirror row_mask:0xf bank_mask:0xf
	v_add_f32_dpp v23, v23, v23 row_mirror row_mask:0xf bank_mask:0xf
	v_pk_fma_f32 v[90:91], v[74:75], v[80:81], v[90:91] op_sel:[1,0,0] op_sel_hi:[1,1,1]
	v_mov_b32_dpp v58, v59 quad_perm:[0,1,2,3] row_mask:0xf bank_mask:0xa
	v_pk_fma_f32 v[2:3], v[68:69], v[22:23], v[84:85] op_sel:[0,0,0] op_sel_hi:[0,1,1] neg_lo:[1,0,0] neg_hi:[1,0,0]
	v_pk_fma_f32 v[4:5], v[68:69], v[22:23], v[86:87] op_sel:[1,0,0] op_sel_hi:[1,1,1] neg_lo:[1,0,0] neg_hi:[1,0,0]
	v_pk_fma_f32 v[6:7], v[70:71], v[22:23], v[88:89] op_sel:[0,0,0] op_sel_hi:[0,1,1] neg_lo:[1,0,0] neg_hi:[1,0,0]
	v_pk_fma_f32 v[8:9], v[70:71], v[22:23], v[90:91] op_sel:[1,0,0] op_sel_hi:[1,1,1] neg_lo:[1,0,0] neg_hi:[1,0,0]
	s_waitcnt lgkmcnt(0)
	ds_read_b128 v[60:63], v20 offset:2816
	ds_read_b128 v[64:67], v20 offset:11008
	ds_read_b64 v[80:81], v21 offset:43776
	ds_read_b128 v[72:75], v20 offset:27392
	ds_read_b128 v[68:71], v20 offset:19200
	ds_read_b128 v[92:95], v20 offset:35584
	v_pk_mul_f32 v[22:23], v[2:3], v[36:37] op_sel:[0,0] op_sel_hi:[1,0]
	v_pk_mul_f32 v[26:27], v[2:3], v[52:53] op_sel:[0,0] op_sel_hi:[1,0]
	v_pk_mul_f32 v[84:85], v[2:3], v[40:41] op_sel:[0,0] op_sel_hi:[1,0]
	v_pk_fma_f32 v[22:23], v[4:5], v[36:37], v[22:23] op_sel:[0,1,0] op_sel_hi:[1,1,1]
	v_pk_fma_f32 v[26:27], v[4:5], v[52:53], v[26:27] op_sel:[0,1,0] op_sel_hi:[1,1,1]
	v_pk_mul_f32 v[86:87], v[4:5], v[40:41] op_sel:[0,1] op_sel_hi:[1,1]
	v_pk_fma_f32 v[22:23], v[6:7], v[38:39], v[22:23] op_sel:[0,0,0] op_sel_hi:[1,0,1]
	v_pk_fma_f32 v[26:27], v[6:7], v[54:55], v[26:27] op_sel:[0,0,0] op_sel_hi:[1,0,1]
	v_pk_mul_f32 v[88:89], v[6:7], v[42:43] op_sel:[0,0] op_sel_hi:[1,0]
	v_pk_fma_f32 v[22:23], v[8:9], v[38:39], v[22:23] op_sel:[0,1,0] op_sel_hi:[1,1,1]
	v_pk_fma_f32 v[26:27], v[8:9], v[54:55], v[26:27] op_sel:[0,1,0] op_sel_hi:[1,1,1]
	v_pk_mul_f32 v[90:91], v[8:9], v[42:43] op_sel:[0,1] op_sel_hi:[1,1]
	v_add_f32_dpp v28, v28, v28 row_ror:8 row_mask:0xf bank_mask:0x3
	v_add_f32_dpp v58, v58, v58 row_ror:8 row_mask:0xf bank_mask:0xc
	v_add_f32_dpp v22, v22, v22 quad_perm:[1,0,3,2] row_mask:0xf bank_mask:0xf
	v_add_f32_dpp v23, v23, v23 quad_perm:[1,0,3,2] row_mask:0xf bank_mask:0xf
	v_pk_fma_f32 v[84:85], v[48:49], v[56:57], v[84:85] op_sel:[0,0,0] op_sel_hi:[0,1,1]
	v_mov_b32_dpp v28, v58 quad_perm:[0,1,2,3] row_mask:0xf bank_mask:0xc
	v_add_f32_dpp v22, v22, v22 quad_perm:[2,3,0,1] row_mask:0xf bank_mask:0xf
	v_add_f32_dpp v23, v23, v23 quad_perm:[2,3,0,1] row_mask:0xf bank_mask:0xf
	v_pk_fma_f32 v[86:87], v[48:49], v[56:57], v[86:87] op_sel:[1,0,0] op_sel_hi:[1,1,1]
	v_add_f32_dpp v28, v28, v28 quad_perm:[1,0,3,2] row_mask:0xf bank_mask:0xf
	v_add_f32_dpp v22, v22, v22 row_half_mirror row_mask:0xf bank_mask:0xf
	v_add_f32_dpp v23, v23, v23 row_half_mirror row_mask:0xf bank_mask:0xf
	v_pk_fma_f32 v[88:89], v[50:51], v[56:57], v[88:89] op_sel:[0,0,0] op_sel_hi:[0,1,1]
	v_add_f32_dpp v28, v28, v28 quad_perm:[2,3,0,1] row_mask:0xf bank_mask:0xf
	v_add_f32_dpp v22, v22, v22 row_mirror row_mask:0xf bank_mask:0xf
	v_add_f32_dpp v23, v23, v23 row_mirror row_mask:0xf bank_mask:0xf
	v_pk_fma_f32 v[90:91], v[50:51], v[56:57], v[90:91] op_sel:[1,0,0] op_sel_hi:[1,1,1]
	v_cndmask_b32_e64 v30, v30, v28, s[10:11]
	v_pk_fma_f32 v[2:3], v[44:45], v[22:23], v[84:85] op_sel:[0,0,0] op_sel_hi:[0,1,1] neg_lo:[1,0,0] neg_hi:[1,0,0]
	v_pk_fma_f32 v[4:5], v[44:45], v[22:23], v[86:87] op_sel:[1,0,0] op_sel_hi:[1,1,1] neg_lo:[1,0,0] neg_hi:[1,0,0]
	v_pk_fma_f32 v[6:7], v[46:47], v[22:23], v[88:89] op_sel:[0,0,0] op_sel_hi:[0,1,1] neg_lo:[1,0,0] neg_hi:[1,0,0]
	v_pk_fma_f32 v[8:9], v[46:47], v[22:23], v[90:91] op_sel:[1,0,0] op_sel_hi:[1,1,1] neg_lo:[1,0,0] neg_hi:[1,0,0]
	s_waitcnt lgkmcnt(0)
	ds_read_b128 v[36:39], v20 offset:3072
	ds_read_b128 v[40:43], v20 offset:11264
	ds_read_b64 v[56:57], v21 offset:44032
	ds_read_b128 v[48:51], v20 offset:27648
	ds_read_b128 v[44:47], v20 offset:19456
	ds_read_b128 v[52:55], v20 offset:35840
	v_pk_mul_f32 v[22:23], v[2:3], v[60:61] op_sel:[0,0] op_sel_hi:[1,0]
	v_pk_mul_f32 v[28:29], v[2:3], v[76:77] op_sel:[0,0] op_sel_hi:[1,0]
	v_pk_mul_f32 v[84:85], v[2:3], v[64:65] op_sel:[0,0] op_sel_hi:[1,0]
	v_pk_fma_f32 v[22:23], v[4:5], v[60:61], v[22:23] op_sel:[0,1,0] op_sel_hi:[1,1,1]
	v_pk_fma_f32 v[28:29], v[4:5], v[76:77], v[28:29] op_sel:[0,1,0] op_sel_hi:[1,1,1]
	v_pk_mul_f32 v[86:87], v[4:5], v[64:65] op_sel:[0,1] op_sel_hi:[1,1]
	v_pk_fma_f32 v[22:23], v[6:7], v[62:63], v[22:23] op_sel:[0,0,0] op_sel_hi:[1,0,1]
	v_pk_fma_f32 v[28:29], v[6:7], v[78:79], v[28:29] op_sel:[0,0,0] op_sel_hi:[1,0,1]
	v_pk_mul_f32 v[88:89], v[6:7], v[66:67] op_sel:[0,0] op_sel_hi:[1,0]
	v_pk_fma_f32 v[22:23], v[8:9], v[62:63], v[22:23] op_sel:[0,1,0] op_sel_hi:[1,1,1]
	v_pk_fma_f32 v[28:29], v[8:9], v[78:79], v[28:29] op_sel:[0,1,0] op_sel_hi:[1,1,1]
	v_pk_mul_f32 v[90:91], v[8:9], v[66:67] op_sel:[0,1] op_sel_hi:[1,1]
	v_add_f32_dpp v24, v24, v24 row_ror:12 row_mask:0xf bank_mask:0x5
	v_add_f32_dpp v25, v25, v25 row_ror:4 row_mask:0xf bank_mask:0xa
	v_add_f32_dpp v22, v22, v22 quad_perm:[1,0,3,2] row_mask:0xf bank_mask:0xf
	v_add_f32_dpp v23, v23, v23 quad_perm:[1,0,3,2] row_mask:0xf bank_mask:0xf
	v_pk_fma_f32 v[84:85], v[72:73], v[80:81], v[84:85] op_sel:[0,0,0] op_sel_hi:[0,1,1]
	v_add_f32_dpp v26, v26, v26 row_ror:12 row_mask:0xf bank_mask:0x5
	v_add_f32_dpp v22, v22, v22 quad_perm:[2,3,0,1] row_mask:0xf bank_mask:0xf
	v_add_f32_dpp v23, v23, v23 quad_perm:[2,3,0,1] row_mask:0xf bank_mask:0xf
	v_pk_fma_f32 v[86:87], v[72:73], v[80:81], v[86:87] op_sel:[1,0,0] op_sel_hi:[1,1,1]
	v_add_f32_dpp v27, v27, v27 row_ror:4 row_mask:0xf bank_mask:0xa
	v_add_f32_dpp v22, v22, v22 row_half_mirror row_mask:0xf bank_mask:0xf
	v_add_f32_dpp v23, v23, v23 row_half_mirror row_mask:0xf bank_mask:0xf
	v_pk_fma_f32 v[88:89], v[74:75], v[80:81], v[88:89] op_sel:[0,0,0] op_sel_hi:[0,1,1]
	v_mov_b32_dpp v24, v25 quad_perm:[0,1,2,3] row_mask:0xf bank_mask:0xa
	v_add_f32_dpp v22, v22, v22 row_mirror row_mask:0xf bank_mask:0xf
	v_add_f32_dpp v23, v23, v23 row_mirror row_mask:0xf bank_mask:0xf
	v_pk_fma_f32 v[90:91], v[74:75], v[80:81], v[90:91] op_sel:[1,0,0] op_sel_hi:[1,1,1]
	v_mov_b32_dpp v26, v27 quad_perm:[0,1,2,3] row_mask:0xf bank_mask:0xa
	v_pk_fma_f32 v[2:3], v[68:69], v[22:23], v[84:85] op_sel:[0,0,0] op_sel_hi:[0,1,1] neg_lo:[1,0,0] neg_hi:[1,0,0]
	v_pk_fma_f32 v[4:5], v[68:69], v[22:23], v[86:87] op_sel:[1,0,0] op_sel_hi:[1,1,1] neg_lo:[1,0,0] neg_hi:[1,0,0]
	v_pk_fma_f32 v[6:7], v[70:71], v[22:23], v[88:89] op_sel:[0,0,0] op_sel_hi:[0,1,1] neg_lo:[1,0,0] neg_hi:[1,0,0]
	v_pk_fma_f32 v[8:9], v[70:71], v[22:23], v[90:91] op_sel:[1,0,0] op_sel_hi:[1,1,1] neg_lo:[1,0,0] neg_hi:[1,0,0]
	s_waitcnt lgkmcnt(0)
	ds_read_b128 v[60:63], v20 offset:3328
	ds_read_b128 v[64:67], v20 offset:11520
	ds_read_b64 v[80:81], v21 offset:44288
	ds_read_b128 v[72:75], v20 offset:27904
	ds_read_b128 v[68:71], v20 offset:19712
	ds_read_b128 v[76:79], v20 offset:36096
	v_pk_mul_f32 v[22:23], v[2:3], v[36:37] op_sel:[0,0] op_sel_hi:[1,0]
	v_pk_mul_f32 v[58:59], v[2:3], v[92:93] op_sel:[0,0] op_sel_hi:[1,0]
	v_pk_mul_f32 v[84:85], v[2:3], v[40:41] op_sel:[0,0] op_sel_hi:[1,0]
	v_pk_fma_f32 v[22:23], v[4:5], v[36:37], v[22:23] op_sel:[0,1,0] op_sel_hi:[1,1,1]
	v_pk_fma_f32 v[58:59], v[4:5], v[92:93], v[58:59] op_sel:[0,1,0] op_sel_hi:[1,1,1]
	v_pk_mul_f32 v[86:87], v[4:5], v[40:41] op_sel:[0,1] op_sel_hi:[1,1]
	v_pk_fma_f32 v[22:23], v[6:7], v[38:39], v[22:23] op_sel:[0,0,0] op_sel_hi:[1,0,1]
	v_pk_fma_f32 v[58:59], v[6:7], v[94:95], v[58:59] op_sel:[0,0,0] op_sel_hi:[1,0,1]
	v_pk_mul_f32 v[88:89], v[6:7], v[42:43] op_sel:[0,0] op_sel_hi:[1,0]
	v_pk_fma_f32 v[22:23], v[8:9], v[38:39], v[22:23] op_sel:[0,1,0] op_sel_hi:[1,1,1]
	v_pk_fma_f32 v[58:59], v[8:9], v[94:95], v[58:59] op_sel:[0,1,0] op_sel_hi:[1,1,1]
	v_pk_mul_f32 v[90:91], v[8:9], v[42:43] op_sel:[0,1] op_sel_hi:[1,1]
	v_add_f32_dpp v24, v24, v24 row_ror:8 row_mask:0xf bank_mask:0x3
	v_add_f32_dpp v26, v26, v26 row_ror:8 row_mask:0xf bank_mask:0xc
	v_add_f32_dpp v22, v22, v22 quad_perm:[1,0,3,2] row_mask:0xf bank_mask:0xf
	v_add_f32_dpp v23, v23, v23 quad_perm:[1,0,3,2] row_mask:0xf bank_mask:0xf
	v_pk_fma_f32 v[84:85], v[48:49], v[56:57], v[84:85] op_sel:[0,0,0] op_sel_hi:[0,1,1]
	v_mov_b32_dpp v24, v26 quad_perm:[0,1,2,3] row_mask:0xf bank_mask:0xc
	v_add_f32_dpp v22, v22, v22 quad_perm:[2,3,0,1] row_mask:0xf bank_mask:0xf
	v_add_f32_dpp v23, v23, v23 quad_perm:[2,3,0,1] row_mask:0xf bank_mask:0xf
	v_pk_fma_f32 v[86:87], v[48:49], v[56:57], v[86:87] op_sel:[1,0,0] op_sel_hi:[1,1,1]
	v_add_f32_dpp v24, v24, v24 quad_perm:[1,0,3,2] row_mask:0xf bank_mask:0xf
	v_add_f32_dpp v22, v22, v22 row_half_mirror row_mask:0xf bank_mask:0xf
	v_add_f32_dpp v23, v23, v23 row_half_mirror row_mask:0xf bank_mask:0xf
	v_pk_fma_f32 v[88:89], v[50:51], v[56:57], v[88:89] op_sel:[0,0,0] op_sel_hi:[0,1,1]
	v_add_f32_dpp v24, v24, v24 quad_perm:[2,3,0,1] row_mask:0xf bank_mask:0xf
	v_add_f32_dpp v22, v22, v22 row_mirror row_mask:0xf bank_mask:0xf
	v_add_f32_dpp v23, v23, v23 row_mirror row_mask:0xf bank_mask:0xf
	v_pk_fma_f32 v[90:91], v[50:51], v[56:57], v[90:91] op_sel:[1,0,0] op_sel_hi:[1,1,1]
	v_cndmask_b32_e64 v31, 0, v24, s[0:1]
	v_pk_fma_f32 v[2:3], v[44:45], v[22:23], v[84:85] op_sel:[0,0,0] op_sel_hi:[0,1,1] neg_lo:[1,0,0] neg_hi:[1,0,0]
	v_pk_fma_f32 v[4:5], v[44:45], v[22:23], v[86:87] op_sel:[1,0,0] op_sel_hi:[1,1,1] neg_lo:[1,0,0] neg_hi:[1,0,0]
	v_pk_fma_f32 v[6:7], v[46:47], v[22:23], v[88:89] op_sel:[0,0,0] op_sel_hi:[0,1,1] neg_lo:[1,0,0] neg_hi:[1,0,0]
	v_pk_fma_f32 v[8:9], v[46:47], v[22:23], v[90:91] op_sel:[1,0,0] op_sel_hi:[1,1,1] neg_lo:[1,0,0] neg_hi:[1,0,0]
	s_waitcnt lgkmcnt(0)
	ds_read_b128 v[36:39], v20 offset:3584
	ds_read_b128 v[40:43], v20 offset:11776
	ds_read_b64 v[56:57], v21 offset:44544
	ds_read_b128 v[48:51], v20 offset:28160
	ds_read_b128 v[44:47], v20 offset:19968
	ds_read_b128 v[92:95], v20 offset:36352
	v_pk_mul_f32 v[22:23], v[2:3], v[60:61] op_sel:[0,0] op_sel_hi:[1,0]
	v_pk_mul_f32 v[24:25], v[2:3], v[52:53] op_sel:[0,0] op_sel_hi:[1,0]
	v_pk_mul_f32 v[84:85], v[2:3], v[64:65] op_sel:[0,0] op_sel_hi:[1,0]
	v_pk_fma_f32 v[22:23], v[4:5], v[60:61], v[22:23] op_sel:[0,1,0] op_sel_hi:[1,1,1]
	v_pk_fma_f32 v[24:25], v[4:5], v[52:53], v[24:25] op_sel:[0,1,0] op_sel_hi:[1,1,1]
	v_pk_mul_f32 v[86:87], v[4:5], v[64:65] op_sel:[0,1] op_sel_hi:[1,1]
	v_pk_fma_f32 v[22:23], v[6:7], v[62:63], v[22:23] op_sel:[0,0,0] op_sel_hi:[1,0,1]
	v_pk_fma_f32 v[24:25], v[6:7], v[54:55], v[24:25] op_sel:[0,0,0] op_sel_hi:[1,0,1]
	v_pk_mul_f32 v[88:89], v[6:7], v[66:67] op_sel:[0,0] op_sel_hi:[1,0]
	v_pk_fma_f32 v[22:23], v[8:9], v[62:63], v[22:23] op_sel:[0,1,0] op_sel_hi:[1,1,1]
	v_pk_fma_f32 v[24:25], v[8:9], v[54:55], v[24:25] op_sel:[0,1,0] op_sel_hi:[1,1,1]
	v_pk_mul_f32 v[90:91], v[8:9], v[66:67] op_sel:[0,1] op_sel_hi:[1,1]
	v_add_f32_dpp v28, v28, v28 row_ror:12 row_mask:0xf bank_mask:0x5
	v_add_f32_dpp v29, v29, v29 row_ror:4 row_mask:0xf bank_mask:0xa
	v_add_f32_dpp v22, v22, v22 quad_perm:[1,0,3,2] row_mask:0xf bank_mask:0xf
	v_add_f32_dpp v23, v23, v23 quad_perm:[1,0,3,2] row_mask:0xf bank_mask:0xf
	v_pk_fma_f32 v[84:85], v[72:73], v[80:81], v[84:85] op_sel:[0,0,0] op_sel_hi:[0,1,1]
	v_add_f32_dpp v58, v58, v58 row_ror:12 row_mask:0xf bank_mask:0x5
	v_add_f32_dpp v22, v22, v22 quad_perm:[2,3,0,1] row_mask:0xf bank_mask:0xf
	v_add_f32_dpp v23, v23, v23 quad_perm:[2,3,0,1] row_mask:0xf bank_mask:0xf
	v_pk_fma_f32 v[86:87], v[72:73], v[80:81], v[86:87] op_sel:[1,0,0] op_sel_hi:[1,1,1]
	v_add_f32_dpp v59, v59, v59 row_ror:4 row_mask:0xf bank_mask:0xa
	v_add_f32_dpp v22, v22, v22 row_half_mirror row_mask:0xf bank_mask:0xf
	v_add_f32_dpp v23, v23, v23 row_half_mirror row_mask:0xf bank_mask:0xf
	v_pk_fma_f32 v[88:89], v[74:75], v[80:81], v[88:89] op_sel:[0,0,0] op_sel_hi:[0,1,1]
	v_mov_b32_dpp v28, v29 quad_perm:[0,1,2,3] row_mask:0xf bank_mask:0xa
	v_add_f32_dpp v22, v22, v22 row_mirror row_mask:0xf bank_mask:0xf
	v_add_f32_dpp v23, v23, v23 row_mirror row_mask:0xf bank_mask:0xf
	v_pk_fma_f32 v[90:91], v[74:75], v[80:81], v[90:91] op_sel:[1,0,0] op_sel_hi:[1,1,1]
	v_mov_b32_dpp v58, v59 quad_perm:[0,1,2,3] row_mask:0xf bank_mask:0xa
	v_pk_fma_f32 v[2:3], v[68:69], v[22:23], v[84:85] op_sel:[0,0,0] op_sel_hi:[0,1,1] neg_lo:[1,0,0] neg_hi:[1,0,0]
	v_pk_fma_f32 v[4:5], v[68:69], v[22:23], v[86:87] op_sel:[1,0,0] op_sel_hi:[1,1,1] neg_lo:[1,0,0] neg_hi:[1,0,0]
	v_pk_fma_f32 v[6:7], v[70:71], v[22:23], v[88:89] op_sel:[0,0,0] op_sel_hi:[0,1,1] neg_lo:[1,0,0] neg_hi:[1,0,0]
	v_pk_fma_f32 v[8:9], v[70:71], v[22:23], v[90:91] op_sel:[1,0,0] op_sel_hi:[1,1,1] neg_lo:[1,0,0] neg_hi:[1,0,0]
	s_waitcnt lgkmcnt(0)
	ds_read_b128 v[60:63], v20 offset:3840
	ds_read_b128 v[64:67], v20 offset:12032
	ds_read_b64 v[80:81], v21 offset:44800
	ds_read_b128 v[72:75], v20 offset:28416
	ds_read_b128 v[68:71], v20 offset:20224
	ds_read_b128 v[52:55], v20 offset:36608
	v_pk_mul_f32 v[22:23], v[2:3], v[36:37] op_sel:[0,0] op_sel_hi:[1,0]
	v_pk_mul_f32 v[26:27], v[2:3], v[76:77] op_sel:[0,0] op_sel_hi:[1,0]
	v_pk_mul_f32 v[84:85], v[2:3], v[40:41] op_sel:[0,0] op_sel_hi:[1,0]
	v_pk_fma_f32 v[22:23], v[4:5], v[36:37], v[22:23] op_sel:[0,1,0] op_sel_hi:[1,1,1]
	v_pk_fma_f32 v[26:27], v[4:5], v[76:77], v[26:27] op_sel:[0,1,0] op_sel_hi:[1,1,1]
	v_pk_mul_f32 v[86:87], v[4:5], v[40:41] op_sel:[0,1] op_sel_hi:[1,1]
	v_pk_fma_f32 v[22:23], v[6:7], v[38:39], v[22:23] op_sel:[0,0,0] op_sel_hi:[1,0,1]
	v_pk_fma_f32 v[26:27], v[6:7], v[78:79], v[26:27] op_sel:[0,0,0] op_sel_hi:[1,0,1]
	v_pk_mul_f32 v[88:89], v[6:7], v[42:43] op_sel:[0,0] op_sel_hi:[1,0]
	v_pk_fma_f32 v[22:23], v[8:9], v[38:39], v[22:23] op_sel:[0,1,0] op_sel_hi:[1,1,1]
	v_pk_fma_f32 v[26:27], v[8:9], v[78:79], v[26:27] op_sel:[0,1,0] op_sel_hi:[1,1,1]
	v_pk_mul_f32 v[90:91], v[8:9], v[42:43] op_sel:[0,1] op_sel_hi:[1,1]
	v_add_f32_dpp v28, v28, v28 row_ror:8 row_mask:0xf bank_mask:0x3
	v_add_f32_dpp v58, v58, v58 row_ror:8 row_mask:0xf bank_mask:0xc
	v_add_f32_dpp v22, v22, v22 quad_perm:[1,0,3,2] row_mask:0xf bank_mask:0xf
	v_add_f32_dpp v23, v23, v23 quad_perm:[1,0,3,2] row_mask:0xf bank_mask:0xf
	v_pk_fma_f32 v[84:85], v[48:49], v[56:57], v[84:85] op_sel:[0,0,0] op_sel_hi:[0,1,1]
	v_mov_b32_dpp v28, v58 quad_perm:[0,1,2,3] row_mask:0xf bank_mask:0xc
	v_add_f32_dpp v22, v22, v22 quad_perm:[2,3,0,1] row_mask:0xf bank_mask:0xf
	v_add_f32_dpp v23, v23, v23 quad_perm:[2,3,0,1] row_mask:0xf bank_mask:0xf
	v_pk_fma_f32 v[86:87], v[48:49], v[56:57], v[86:87] op_sel:[1,0,0] op_sel_hi:[1,1,1]
	v_add_f32_dpp v28, v28, v28 quad_perm:[1,0,3,2] row_mask:0xf bank_mask:0xf
	v_add_f32_dpp v22, v22, v22 row_half_mirror row_mask:0xf bank_mask:0xf
	v_add_f32_dpp v23, v23, v23 row_half_mirror row_mask:0xf bank_mask:0xf
	v_pk_fma_f32 v[88:89], v[50:51], v[56:57], v[88:89] op_sel:[0,0,0] op_sel_hi:[0,1,1]
	v_add_f32_dpp v28, v28, v28 quad_perm:[2,3,0,1] row_mask:0xf bank_mask:0xf
	v_add_f32_dpp v22, v22, v22 row_mirror row_mask:0xf bank_mask:0xf
	v_add_f32_dpp v23, v23, v23 row_mirror row_mask:0xf bank_mask:0xf
	v_pk_fma_f32 v[90:91], v[50:51], v[56:57], v[90:91] op_sel:[1,0,0] op_sel_hi:[1,1,1]
	v_cndmask_b32_e64 v31, v31, v28, s[6:7]
	v_pk_fma_f32 v[2:3], v[44:45], v[22:23], v[84:85] op_sel:[0,0,0] op_sel_hi:[0,1,1] neg_lo:[1,0,0] neg_hi:[1,0,0]
	v_pk_fma_f32 v[4:5], v[44:45], v[22:23], v[86:87] op_sel:[1,0,0] op_sel_hi:[1,1,1] neg_lo:[1,0,0] neg_hi:[1,0,0]
	v_pk_fma_f32 v[6:7], v[46:47], v[22:23], v[88:89] op_sel:[0,0,0] op_sel_hi:[0,1,1] neg_lo:[1,0,0] neg_hi:[1,0,0]
	v_pk_fma_f32 v[8:9], v[46:47], v[22:23], v[90:91] op_sel:[1,0,0] op_sel_hi:[1,1,1] neg_lo:[1,0,0] neg_hi:[1,0,0]
	s_waitcnt lgkmcnt(0)
	ds_read_b128 v[36:39], v20 offset:4096
	ds_read_b128 v[40:43], v20 offset:12288
	ds_read_b64 v[56:57], v21 offset:45056
	ds_read_b128 v[48:51], v20 offset:28672
	ds_read_b128 v[44:47], v20 offset:20480
	ds_read_b128 v[76:79], v20 offset:36864
	v_pk_mul_f32 v[22:23], v[2:3], v[60:61] op_sel:[0,0] op_sel_hi:[1,0]
	v_pk_mul_f32 v[28:29], v[2:3], v[92:93] op_sel:[0,0] op_sel_hi:[1,0]
	v_pk_mul_f32 v[84:85], v[2:3], v[64:65] op_sel:[0,0] op_sel_hi:[1,0]
	v_pk_fma_f32 v[22:23], v[4:5], v[60:61], v[22:23] op_sel:[0,1,0] op_sel_hi:[1,1,1]
	v_pk_fma_f32 v[28:29], v[4:5], v[92:93], v[28:29] op_sel:[0,1,0] op_sel_hi:[1,1,1]
	v_pk_mul_f32 v[86:87], v[4:5], v[64:65] op_sel:[0,1] op_sel_hi:[1,1]
	v_pk_fma_f32 v[22:23], v[6:7], v[62:63], v[22:23] op_sel:[0,0,0] op_sel_hi:[1,0,1]
	v_pk_fma_f32 v[28:29], v[6:7], v[94:95], v[28:29] op_sel:[0,0,0] op_sel_hi:[1,0,1]
	v_pk_mul_f32 v[88:89], v[6:7], v[66:67] op_sel:[0,0] op_sel_hi:[1,0]
	v_pk_fma_f32 v[22:23], v[8:9], v[62:63], v[22:23] op_sel:[0,1,0] op_sel_hi:[1,1,1]
	v_pk_fma_f32 v[28:29], v[8:9], v[94:95], v[28:29] op_sel:[0,1,0] op_sel_hi:[1,1,1]
	v_pk_mul_f32 v[90:91], v[8:9], v[66:67] op_sel:[0,1] op_sel_hi:[1,1]
	v_add_f32_dpp v24, v24, v24 row_ror:12 row_mask:0xf bank_mask:0x5
	v_add_f32_dpp v25, v25, v25 row_ror:4 row_mask:0xf bank_mask:0xa
	v_add_f32_dpp v22, v22, v22 quad_perm:[1,0,3,2] row_mask:0xf bank_mask:0xf
	v_add_f32_dpp v23, v23, v23 quad_perm:[1,0,3,2] row_mask:0xf bank_mask:0xf
	v_pk_fma_f32 v[84:85], v[72:73], v[80:81], v[84:85] op_sel:[0,0,0] op_sel_hi:[0,1,1]
	v_add_f32_dpp v26, v26, v26 row_ror:12 row_mask:0xf bank_mask:0x5
	v_add_f32_dpp v22, v22, v22 quad_perm:[2,3,0,1] row_mask:0xf bank_mask:0xf
	v_add_f32_dpp v23, v23, v23 quad_perm:[2,3,0,1] row_mask:0xf bank_mask:0xf
	v_pk_fma_f32 v[86:87], v[72:73], v[80:81], v[86:87] op_sel:[1,0,0] op_sel_hi:[1,1,1]
	v_add_f32_dpp v27, v27, v27 row_ror:4 row_mask:0xf bank_mask:0xa
	v_add_f32_dpp v22, v22, v22 row_half_mirror row_mask:0xf bank_mask:0xf
	v_add_f32_dpp v23, v23, v23 row_half_mirror row_mask:0xf bank_mask:0xf
	v_pk_fma_f32 v[88:89], v[74:75], v[80:81], v[88:89] op_sel:[0,0,0] op_sel_hi:[0,1,1]
	v_mov_b32_dpp v24, v25 quad_perm:[0,1,2,3] row_mask:0xf bank_mask:0xa
	v_add_f32_dpp v22, v22, v22 row_mirror row_mask:0xf bank_mask:0xf
	v_add_f32_dpp v23, v23, v23 row_mirror row_mask:0xf bank_mask:0xf
	v_pk_fma_f32 v[90:91], v[74:75], v[80:81], v[90:91] op_sel:[1,0,0] op_sel_hi:[1,1,1]
	v_mov_b32_dpp v26, v27 quad_perm:[0,1,2,3] row_mask:0xf bank_mask:0xa
	v_pk_fma_f32 v[2:3], v[68:69], v[22:23], v[84:85] op_sel:[0,0,0] op_sel_hi:[0,1,1] neg_lo:[1,0,0] neg_hi:[1,0,0]
	v_pk_fma_f32 v[4:5], v[68:69], v[22:23], v[86:87] op_sel:[1,0,0] op_sel_hi:[1,1,1] neg_lo:[1,0,0] neg_hi:[1,0,0]
	v_pk_fma_f32 v[6:7], v[70:71], v[22:23], v[88:89] op_sel:[0,0,0] op_sel_hi:[0,1,1] neg_lo:[1,0,0] neg_hi:[1,0,0]
	v_pk_fma_f32 v[8:9], v[70:71], v[22:23], v[90:91] op_sel:[1,0,0] op_sel_hi:[1,1,1] neg_lo:[1,0,0] neg_hi:[1,0,0]
	s_waitcnt lgkmcnt(0)
	ds_read_b128 v[60:63], v20 offset:4352
	ds_read_b128 v[64:67], v20 offset:12544
	ds_read_b64 v[80:81], v21 offset:45312
	ds_read_b128 v[72:75], v20 offset:28928
	ds_read_b128 v[68:71], v20 offset:20736
	ds_read_b128 v[92:95], v20 offset:37120
	v_pk_mul_f32 v[22:23], v[2:3], v[36:37] op_sel:[0,0] op_sel_hi:[1,0]
	v_pk_mul_f32 v[58:59], v[2:3], v[52:53] op_sel:[0,0] op_sel_hi:[1,0]
	v_pk_mul_f32 v[84:85], v[2:3], v[40:41] op_sel:[0,0] op_sel_hi:[1,0]
	v_pk_fma_f32 v[22:23], v[4:5], v[36:37], v[22:23] op_sel:[0,1,0] op_sel_hi:[1,1,1]
	v_pk_fma_f32 v[58:59], v[4:5], v[52:53], v[58:59] op_sel:[0,1,0] op_sel_hi:[1,1,1]
	v_pk_mul_f32 v[86:87], v[4:5], v[40:41] op_sel:[0,1] op_sel_hi:[1,1]
	v_pk_fma_f32 v[22:23], v[6:7], v[38:39], v[22:23] op_sel:[0,0,0] op_sel_hi:[1,0,1]
	v_pk_fma_f32 v[58:59], v[6:7], v[54:55], v[58:59] op_sel:[0,0,0] op_sel_hi:[1,0,1]
	v_pk_mul_f32 v[88:89], v[6:7], v[42:43] op_sel:[0,0] op_sel_hi:[1,0]
	v_pk_fma_f32 v[22:23], v[8:9], v[38:39], v[22:23] op_sel:[0,1,0] op_sel_hi:[1,1,1]
	v_pk_fma_f32 v[58:59], v[8:9], v[54:55], v[58:59] op_sel:[0,1,0] op_sel_hi:[1,1,1]
	v_pk_mul_f32 v[90:91], v[8:9], v[42:43] op_sel:[0,1] op_sel_hi:[1,1]
	v_add_f32_dpp v24, v24, v24 row_ror:8 row_mask:0xf bank_mask:0x3
	v_add_f32_dpp v26, v26, v26 row_ror:8 row_mask:0xf bank_mask:0xc
	v_add_f32_dpp v22, v22, v22 quad_perm:[1,0,3,2] row_mask:0xf bank_mask:0xf
	v_add_f32_dpp v23, v23, v23 quad_perm:[1,0,3,2] row_mask:0xf bank_mask:0xf
	v_pk_fma_f32 v[84:85], v[48:49], v[56:57], v[84:85] op_sel:[0,0,0] op_sel_hi:[0,1,1]
	v_mov_b32_dpp v24, v26 quad_perm:[0,1,2,3] row_mask:0xf bank_mask:0xc
	v_add_f32_dpp v22, v22, v22 quad_perm:[2,3,0,1] row_mask:0xf bank_mask:0xf
	v_add_f32_dpp v23, v23, v23 quad_perm:[2,3,0,1] row_mask:0xf bank_mask:0xf
	v_pk_fma_f32 v[86:87], v[48:49], v[56:57], v[86:87] op_sel:[1,0,0] op_sel_hi:[1,1,1]
	v_add_f32_dpp v24, v24, v24 quad_perm:[1,0,3,2] row_mask:0xf bank_mask:0xf
	v_add_f32_dpp v22, v22, v22 row_half_mirror row_mask:0xf bank_mask:0xf
	v_add_f32_dpp v23, v23, v23 row_half_mirror row_mask:0xf bank_mask:0xf
	v_pk_fma_f32 v[88:89], v[50:51], v[56:57], v[88:89] op_sel:[0,0,0] op_sel_hi:[0,1,1]
	v_add_f32_dpp v24, v24, v24 quad_perm:[2,3,0,1] row_mask:0xf bank_mask:0xf
	v_add_f32_dpp v22, v22, v22 row_mirror row_mask:0xf bank_mask:0xf
	v_add_f32_dpp v23, v23, v23 row_mirror row_mask:0xf bank_mask:0xf
	v_pk_fma_f32 v[90:91], v[50:51], v[56:57], v[90:91] op_sel:[1,0,0] op_sel_hi:[1,1,1]
	v_cndmask_b32_e64 v31, v31, v24, s[8:9]
	v_pk_fma_f32 v[2:3], v[44:45], v[22:23], v[84:85] op_sel:[0,0,0] op_sel_hi:[0,1,1] neg_lo:[1,0,0] neg_hi:[1,0,0]
	v_pk_fma_f32 v[4:5], v[44:45], v[22:23], v[86:87] op_sel:[1,0,0] op_sel_hi:[1,1,1] neg_lo:[1,0,0] neg_hi:[1,0,0]
	v_pk_fma_f32 v[6:7], v[46:47], v[22:23], v[88:89] op_sel:[0,0,0] op_sel_hi:[0,1,1] neg_lo:[1,0,0] neg_hi:[1,0,0]
	v_pk_fma_f32 v[8:9], v[46:47], v[22:23], v[90:91] op_sel:[1,0,0] op_sel_hi:[1,1,1] neg_lo:[1,0,0] neg_hi:[1,0,0]
	s_waitcnt lgkmcnt(0)
	ds_read_b128 v[36:39], v20 offset:4608
	ds_read_b128 v[40:43], v20 offset:12800
	ds_read_b64 v[56:57], v21 offset:45568
	ds_read_b128 v[48:51], v20 offset:29184
	ds_read_b128 v[44:47], v20 offset:20992
	ds_read_b128 v[52:55], v20 offset:37376
	v_pk_mul_f32 v[22:23], v[2:3], v[60:61] op_sel:[0,0] op_sel_hi:[1,0]
	v_pk_mul_f32 v[24:25], v[2:3], v[76:77] op_sel:[0,0] op_sel_hi:[1,0]
	v_pk_mul_f32 v[84:85], v[2:3], v[64:65] op_sel:[0,0] op_sel_hi:[1,0]
	v_pk_fma_f32 v[22:23], v[4:5], v[60:61], v[22:23] op_sel:[0,1,0] op_sel_hi:[1,1,1]
	v_pk_fma_f32 v[24:25], v[4:5], v[76:77], v[24:25] op_sel:[0,1,0] op_sel_hi:[1,1,1]
	v_pk_mul_f32 v[86:87], v[4:5], v[64:65] op_sel:[0,1] op_sel_hi:[1,1]
	v_pk_fma_f32 v[22:23], v[6:7], v[62:63], v[22:23] op_sel:[0,0,0] op_sel_hi:[1,0,1]
	v_pk_fma_f32 v[24:25], v[6:7], v[78:79], v[24:25] op_sel:[0,0,0] op_sel_hi:[1,0,1]
	v_pk_mul_f32 v[88:89], v[6:7], v[66:67] op_sel:[0,0] op_sel_hi:[1,0]
	v_pk_fma_f32 v[22:23], v[8:9], v[62:63], v[22:23] op_sel:[0,1,0] op_sel_hi:[1,1,1]
	v_pk_fma_f32 v[24:25], v[8:9], v[78:79], v[24:25] op_sel:[0,1,0] op_sel_hi:[1,1,1]
	v_pk_mul_f32 v[90:91], v[8:9], v[66:67] op_sel:[0,1] op_sel_hi:[1,1]
	v_add_f32_dpp v28, v28, v28 row_ror:12 row_mask:0xf bank_mask:0x5
	v_add_f32_dpp v29, v29, v29 row_ror:4 row_mask:0xf bank_mask:0xa
	v_add_f32_dpp v22, v22, v22 quad_perm:[1,0,3,2] row_mask:0xf bank_mask:0xf
	v_add_f32_dpp v23, v23, v23 quad_perm:[1,0,3,2] row_mask:0xf bank_mask:0xf
	v_pk_fma_f32 v[84:85], v[72:73], v[80:81], v[84:85] op_sel:[0,0,0] op_sel_hi:[0,1,1]
	v_add_f32_dpp v58, v58, v58 row_ror:12 row_mask:0xf bank_mask:0x5
	v_add_f32_dpp v22, v22, v22 quad_perm:[2,3,0,1] row_mask:0xf bank_mask:0xf
	v_add_f32_dpp v23, v23, v23 quad_perm:[2,3,0,1] row_mask:0xf bank_mask:0xf
	v_pk_fma_f32 v[86:87], v[72:73], v[80:81], v[86:87] op_sel:[1,0,0] op_sel_hi:[1,1,1]
	v_add_f32_dpp v59, v59, v59 row_ror:4 row_mask:0xf bank_mask:0xa
	v_add_f32_dpp v22, v22, v22 row_half_mirror row_mask:0xf bank_mask:0xf
	v_add_f32_dpp v23, v23, v23 row_half_mirror row_mask:0xf bank_mask:0xf
	v_pk_fma_f32 v[88:89], v[74:75], v[80:81], v[88:89] op_sel:[0,0,0] op_sel_hi:[0,1,1]
	v_mov_b32_dpp v28, v29 quad_perm:[0,1,2,3] row_mask:0xf bank_mask:0xa
	v_add_f32_dpp v22, v22, v22 row_mirror row_mask:0xf bank_mask:0xf
	v_add_f32_dpp v23, v23, v23 row_mirror row_mask:0xf bank_mask:0xf
	v_pk_fma_f32 v[90:91], v[74:75], v[80:81], v[90:91] op_sel:[1,0,0] op_sel_hi:[1,1,1]
	v_mov_b32_dpp v58, v59 quad_perm:[0,1,2,3] row_mask:0xf bank_mask:0xa
	v_pk_fma_f32 v[2:3], v[68:69], v[22:23], v[84:85] op_sel:[0,0,0] op_sel_hi:[0,1,1] neg_lo:[1,0,0] neg_hi:[1,0,0]
	v_pk_fma_f32 v[4:5], v[68:69], v[22:23], v[86:87] op_sel:[1,0,0] op_sel_hi:[1,1,1] neg_lo:[1,0,0] neg_hi:[1,0,0]
	v_pk_fma_f32 v[6:7], v[70:71], v[22:23], v[88:89] op_sel:[0,0,0] op_sel_hi:[0,1,1] neg_lo:[1,0,0] neg_hi:[1,0,0]
	v_pk_fma_f32 v[8:9], v[70:71], v[22:23], v[90:91] op_sel:[1,0,0] op_sel_hi:[1,1,1] neg_lo:[1,0,0] neg_hi:[1,0,0]
	s_waitcnt lgkmcnt(0)
	ds_read_b128 v[60:63], v20 offset:4864
	ds_read_b128 v[64:67], v20 offset:13056
	ds_read_b64 v[80:81], v21 offset:45824
	ds_read_b128 v[72:75], v20 offset:29440
	ds_read_b128 v[68:71], v20 offset:21248
	ds_read_b128 v[76:79], v20 offset:37632
	v_pk_mul_f32 v[22:23], v[2:3], v[36:37] op_sel:[0,0] op_sel_hi:[1,0]
	v_pk_mul_f32 v[26:27], v[2:3], v[92:93] op_sel:[0,0] op_sel_hi:[1,0]
	v_pk_mul_f32 v[84:85], v[2:3], v[40:41] op_sel:[0,0] op_sel_hi:[1,0]
	v_pk_fma_f32 v[22:23], v[4:5], v[36:37], v[22:23] op_sel:[0,1,0] op_sel_hi:[1,1,1]
	v_pk_fma_f32 v[26:27], v[4:5], v[92:93], v[26:27] op_sel:[0,1,0] op_sel_hi:[1,1,1]
	v_pk_mul_f32 v[86:87], v[4:5], v[40:41] op_sel:[0,1] op_sel_hi:[1,1]
	v_pk_fma_f32 v[22:23], v[6:7], v[38:39], v[22:23] op_sel:[0,0,0] op_sel_hi:[1,0,1]
	v_pk_fma_f32 v[26:27], v[6:7], v[94:95], v[26:27] op_sel:[0,0,0] op_sel_hi:[1,0,1]
	v_pk_mul_f32 v[88:89], v[6:7], v[42:43] op_sel:[0,0] op_sel_hi:[1,0]
	v_pk_fma_f32 v[22:23], v[8:9], v[38:39], v[22:23] op_sel:[0,1,0] op_sel_hi:[1,1,1]
	v_pk_fma_f32 v[26:27], v[8:9], v[94:95], v[26:27] op_sel:[0,1,0] op_sel_hi:[1,1,1]
	v_pk_mul_f32 v[90:91], v[8:9], v[42:43] op_sel:[0,1] op_sel_hi:[1,1]
	v_add_f32_dpp v28, v28, v28 row_ror:8 row_mask:0xf bank_mask:0x3
	v_add_f32_dpp v58, v58, v58 row_ror:8 row_mask:0xf bank_mask:0xc
	v_add_f32_dpp v22, v22, v22 quad_perm:[1,0,3,2] row_mask:0xf bank_mask:0xf
	v_add_f32_dpp v23, v23, v23 quad_perm:[1,0,3,2] row_mask:0xf bank_mask:0xf
	v_pk_fma_f32 v[84:85], v[48:49], v[56:57], v[84:85] op_sel:[0,0,0] op_sel_hi:[0,1,1]
	v_mov_b32_dpp v28, v58 quad_perm:[0,1,2,3] row_mask:0xf bank_mask:0xc
	v_add_f32_dpp v22, v22, v22 quad_perm:[2,3,0,1] row_mask:0xf bank_mask:0xf
	v_add_f32_dpp v23, v23, v23 quad_perm:[2,3,0,1] row_mask:0xf bank_mask:0xf
	v_pk_fma_f32 v[86:87], v[48:49], v[56:57], v[86:87] op_sel:[1,0,0] op_sel_hi:[1,1,1]
	v_add_f32_dpp v28, v28, v28 quad_perm:[1,0,3,2] row_mask:0xf bank_mask:0xf
	v_add_f32_dpp v22, v22, v22 row_half_mirror row_mask:0xf bank_mask:0xf
	v_add_f32_dpp v23, v23, v23 row_half_mirror row_mask:0xf bank_mask:0xf
	v_pk_fma_f32 v[88:89], v[50:51], v[56:57], v[88:89] op_sel:[0,0,0] op_sel_hi:[0,1,1]
	v_add_f32_dpp v28, v28, v28 quad_perm:[2,3,0,1] row_mask:0xf bank_mask:0xf
	v_add_f32_dpp v22, v22, v22 row_mirror row_mask:0xf bank_mask:0xf
	v_add_f32_dpp v23, v23, v23 row_mirror row_mask:0xf bank_mask:0xf
	v_pk_fma_f32 v[90:91], v[50:51], v[56:57], v[90:91] op_sel:[1,0,0] op_sel_hi:[1,1,1]
	v_cndmask_b32_e64 v31, v31, v28, s[10:11]
	v_pk_fma_f32 v[2:3], v[44:45], v[22:23], v[84:85] op_sel:[0,0,0] op_sel_hi:[0,1,1] neg_lo:[1,0,0] neg_hi:[1,0,0]
	v_pk_fma_f32 v[4:5], v[44:45], v[22:23], v[86:87] op_sel:[1,0,0] op_sel_hi:[1,1,1] neg_lo:[1,0,0] neg_hi:[1,0,0]
	v_pk_fma_f32 v[6:7], v[46:47], v[22:23], v[88:89] op_sel:[0,0,0] op_sel_hi:[0,1,1] neg_lo:[1,0,0] neg_hi:[1,0,0]
	v_pk_fma_f32 v[8:9], v[46:47], v[22:23], v[90:91] op_sel:[1,0,0] op_sel_hi:[1,1,1] neg_lo:[1,0,0] neg_hi:[1,0,0]
	s_waitcnt lgkmcnt(0)
	ds_read_b128 v[36:39], v20 offset:5120
	ds_read_b128 v[40:43], v20 offset:13312
	ds_read_b64 v[56:57], v21 offset:46080
	ds_read_b128 v[48:51], v20 offset:29696
	ds_read_b128 v[44:47], v20 offset:21504
	ds_read_b128 v[92:95], v20 offset:37888
	v_pk_mul_f32 v[22:23], v[2:3], v[60:61] op_sel:[0,0] op_sel_hi:[1,0]
	v_pk_mul_f32 v[28:29], v[2:3], v[52:53] op_sel:[0,0] op_sel_hi:[1,0]
	v_pk_mul_f32 v[84:85], v[2:3], v[64:65] op_sel:[0,0] op_sel_hi:[1,0]
	v_pk_fma_f32 v[22:23], v[4:5], v[60:61], v[22:23] op_sel:[0,1,0] op_sel_hi:[1,1,1]
	v_pk_fma_f32 v[28:29], v[4:5], v[52:53], v[28:29] op_sel:[0,1,0] op_sel_hi:[1,1,1]
	v_pk_mul_f32 v[86:87], v[4:5], v[64:65] op_sel:[0,1] op_sel_hi:[1,1]
	v_pk_fma_f32 v[22:23], v[6:7], v[62:63], v[22:23] op_sel:[0,0,0] op_sel_hi:[1,0,1]
	v_pk_fma_f32 v[28:29], v[6:7], v[54:55], v[28:29] op_sel:[0,0,0] op_sel_hi:[1,0,1]
	v_pk_mul_f32 v[88:89], v[6:7], v[66:67] op_sel:[0,0] op_sel_hi:[1,0]
	v_pk_fma_f32 v[22:23], v[8:9], v[62:63], v[22:23] op_sel:[0,1,0] op_sel_hi:[1,1,1]
	v_pk_fma_f32 v[28:29], v[8:9], v[54:55], v[28:29] op_sel:[0,1,0] op_sel_hi:[1,1,1]
	v_pk_mul_f32 v[90:91], v[8:9], v[66:67] op_sel:[0,1] op_sel_hi:[1,1]
	v_add_f32_dpp v24, v24, v24 row_ror:12 row_mask:0xf bank_mask:0x5
	v_add_f32_dpp v25, v25, v25 row_ror:4 row_mask:0xf bank_mask:0xa
	v_add_f32_dpp v22, v22, v22 quad_perm:[1,0,3,2] row_mask:0xf bank_mask:0xf
	v_add_f32_dpp v23, v23, v23 quad_perm:[1,0,3,2] row_mask:0xf bank_mask:0xf
	v_pk_fma_f32 v[84:85], v[72:73], v[80:81], v[84:85] op_sel:[0,0,0] op_sel_hi:[0,1,1]
	v_add_f32_dpp v26, v26, v26 row_ror:12 row_mask:0xf bank_mask:0x5
	v_add_f32_dpp v22, v22, v22 quad_perm:[2,3,0,1] row_mask:0xf bank_mask:0xf
	v_add_f32_dpp v23, v23, v23 quad_perm:[2,3,0,1] row_mask:0xf bank_mask:0xf
	v_pk_fma_f32 v[86:87], v[72:73], v[80:81], v[86:87] op_sel:[1,0,0] op_sel_hi:[1,1,1]
	v_add_f32_dpp v27, v27, v27 row_ror:4 row_mask:0xf bank_mask:0xa
	v_add_f32_dpp v22, v22, v22 row_half_mirror row_mask:0xf bank_mask:0xf
	v_add_f32_dpp v23, v23, v23 row_half_mirror row_mask:0xf bank_mask:0xf
	v_pk_fma_f32 v[88:89], v[74:75], v[80:81], v[88:89] op_sel:[0,0,0] op_sel_hi:[0,1,1]
	v_mov_b32_dpp v24, v25 quad_perm:[0,1,2,3] row_mask:0xf bank_mask:0xa
	v_add_f32_dpp v22, v22, v22 row_mirror row_mask:0xf bank_mask:0xf
	v_add_f32_dpp v23, v23, v23 row_mirror row_mask:0xf bank_mask:0xf
	v_pk_fma_f32 v[90:91], v[74:75], v[80:81], v[90:91] op_sel:[1,0,0] op_sel_hi:[1,1,1]
	v_mov_b32_dpp v26, v27 quad_perm:[0,1,2,3] row_mask:0xf bank_mask:0xa
	v_pk_fma_f32 v[2:3], v[68:69], v[22:23], v[84:85] op_sel:[0,0,0] op_sel_hi:[0,1,1] neg_lo:[1,0,0] neg_hi:[1,0,0]
	v_pk_fma_f32 v[4:5], v[68:69], v[22:23], v[86:87] op_sel:[1,0,0] op_sel_hi:[1,1,1] neg_lo:[1,0,0] neg_hi:[1,0,0]
	v_pk_fma_f32 v[6:7], v[70:71], v[22:23], v[88:89] op_sel:[0,0,0] op_sel_hi:[0,1,1] neg_lo:[1,0,0] neg_hi:[1,0,0]
	v_pk_fma_f32 v[8:9], v[70:71], v[22:23], v[90:91] op_sel:[1,0,0] op_sel_hi:[1,1,1] neg_lo:[1,0,0] neg_hi:[1,0,0]
	s_waitcnt lgkmcnt(0)
	ds_read_b128 v[60:63], v20 offset:5376
	ds_read_b128 v[64:67], v20 offset:13568
	ds_read_b64 v[80:81], v21 offset:46336
	ds_read_b128 v[72:75], v20 offset:29952
	ds_read_b128 v[68:71], v20 offset:21760
	ds_read_b128 v[52:55], v20 offset:38144
	v_pk_mul_f32 v[22:23], v[2:3], v[36:37] op_sel:[0,0] op_sel_hi:[1,0]
	v_pk_mul_f32 v[58:59], v[2:3], v[76:77] op_sel:[0,0] op_sel_hi:[1,0]
	v_pk_mul_f32 v[84:85], v[2:3], v[40:41] op_sel:[0,0] op_sel_hi:[1,0]
	v_pk_fma_f32 v[22:23], v[4:5], v[36:37], v[22:23] op_sel:[0,1,0] op_sel_hi:[1,1,1]
	v_pk_fma_f32 v[58:59], v[4:5], v[76:77], v[58:59] op_sel:[0,1,0] op_sel_hi:[1,1,1]
	v_pk_mul_f32 v[86:87], v[4:5], v[40:41] op_sel:[0,1] op_sel_hi:[1,1]
	v_pk_fma_f32 v[22:23], v[6:7], v[38:39], v[22:23] op_sel:[0,0,0] op_sel_hi:[1,0,1]
	v_pk_fma_f32 v[58:59], v[6:7], v[78:79], v[58:59] op_sel:[0,0,0] op_sel_hi:[1,0,1]
	v_pk_mul_f32 v[88:89], v[6:7], v[42:43] op_sel:[0,0] op_sel_hi:[1,0]
	v_pk_fma_f32 v[22:23], v[8:9], v[38:39], v[22:23] op_sel:[0,1,0] op_sel_hi:[1,1,1]
	v_pk_fma_f32 v[58:59], v[8:9], v[78:79], v[58:59] op_sel:[0,1,0] op_sel_hi:[1,1,1]
	v_pk_mul_f32 v[90:91], v[8:9], v[42:43] op_sel:[0,1] op_sel_hi:[1,1]
	v_add_f32_dpp v24, v24, v24 row_ror:8 row_mask:0xf bank_mask:0x3
	v_add_f32_dpp v26, v26, v26 row_ror:8 row_mask:0xf bank_mask:0xc
	v_add_f32_dpp v22, v22, v22 quad_perm:[1,0,3,2] row_mask:0xf bank_mask:0xf
	v_add_f32_dpp v23, v23, v23 quad_perm:[1,0,3,2] row_mask:0xf bank_mask:0xf
	v_pk_fma_f32 v[84:85], v[48:49], v[56:57], v[84:85] op_sel:[0,0,0] op_sel_hi:[0,1,1]
	v_mov_b32_dpp v24, v26 quad_perm:[0,1,2,3] row_mask:0xf bank_mask:0xc
	v_add_f32_dpp v22, v22, v22 quad_perm:[2,3,0,1] row_mask:0xf bank_mask:0xf
	v_add_f32_dpp v23, v23, v23 quad_perm:[2,3,0,1] row_mask:0xf bank_mask:0xf
	v_pk_fma_f32 v[86:87], v[48:49], v[56:57], v[86:87] op_sel:[1,0,0] op_sel_hi:[1,1,1]
	v_add_f32_dpp v24, v24, v24 quad_perm:[1,0,3,2] row_mask:0xf bank_mask:0xf
	v_add_f32_dpp v22, v22, v22 row_half_mirror row_mask:0xf bank_mask:0xf
	v_add_f32_dpp v23, v23, v23 row_half_mirror row_mask:0xf bank_mask:0xf
	v_pk_fma_f32 v[88:89], v[50:51], v[56:57], v[88:89] op_sel:[0,0,0] op_sel_hi:[0,1,1]
	v_add_f32_dpp v24, v24, v24 quad_perm:[2,3,0,1] row_mask:0xf bank_mask:0xf
	v_add_f32_dpp v22, v22, v22 row_mirror row_mask:0xf bank_mask:0xf
	v_add_f32_dpp v23, v23, v23 row_mirror row_mask:0xf bank_mask:0xf
	v_pk_fma_f32 v[90:91], v[50:51], v[56:57], v[90:91] op_sel:[1,0,0] op_sel_hi:[1,1,1]
	v_cndmask_b32_e64 v32, 0, v24, s[0:1]
	v_pk_fma_f32 v[2:3], v[44:45], v[22:23], v[84:85] op_sel:[0,0,0] op_sel_hi:[0,1,1] neg_lo:[1,0,0] neg_hi:[1,0,0]
	v_pk_fma_f32 v[4:5], v[44:45], v[22:23], v[86:87] op_sel:[1,0,0] op_sel_hi:[1,1,1] neg_lo:[1,0,0] neg_hi:[1,0,0]
	v_pk_fma_f32 v[6:7], v[46:47], v[22:23], v[88:89] op_sel:[0,0,0] op_sel_hi:[0,1,1] neg_lo:[1,0,0] neg_hi:[1,0,0]
	v_pk_fma_f32 v[8:9], v[46:47], v[22:23], v[90:91] op_sel:[1,0,0] op_sel_hi:[1,1,1] neg_lo:[1,0,0] neg_hi:[1,0,0]
	s_waitcnt lgkmcnt(0)
	ds_read_b128 v[36:39], v20 offset:5632
	ds_read_b128 v[40:43], v20 offset:13824
	ds_read_b64 v[56:57], v21 offset:46592
	ds_read_b128 v[48:51], v20 offset:30208
	ds_read_b128 v[44:47], v20 offset:22016
	ds_read_b128 v[76:79], v20 offset:38400
	v_pk_mul_f32 v[22:23], v[2:3], v[60:61] op_sel:[0,0] op_sel_hi:[1,0]
	v_pk_mul_f32 v[24:25], v[2:3], v[92:93] op_sel:[0,0] op_sel_hi:[1,0]
	v_pk_mul_f32 v[84:85], v[2:3], v[64:65] op_sel:[0,0] op_sel_hi:[1,0]
	v_pk_fma_f32 v[22:23], v[4:5], v[60:61], v[22:23] op_sel:[0,1,0] op_sel_hi:[1,1,1]
	v_pk_fma_f32 v[24:25], v[4:5], v[92:93], v[24:25] op_sel:[0,1,0] op_sel_hi:[1,1,1]
	v_pk_mul_f32 v[86:87], v[4:5], v[64:65] op_sel:[0,1] op_sel_hi:[1,1]
	v_pk_fma_f32 v[22:23], v[6:7], v[62:63], v[22:23] op_sel:[0,0,0] op_sel_hi:[1,0,1]
	v_pk_fma_f32 v[24:25], v[6:7], v[94:95], v[24:25] op_sel:[0,0,0] op_sel_hi:[1,0,1]
	v_pk_mul_f32 v[88:89], v[6:7], v[66:67] op_sel:[0,0] op_sel_hi:[1,0]
	v_pk_fma_f32 v[22:23], v[8:9], v[62:63], v[22:23] op_sel:[0,1,0] op_sel_hi:[1,1,1]
	v_pk_fma_f32 v[24:25], v[8:9], v[94:95], v[24:25] op_sel:[0,1,0] op_sel_hi:[1,1,1]
	v_pk_mul_f32 v[90:91], v[8:9], v[66:67] op_sel:[0,1] op_sel_hi:[1,1]
	v_add_f32_dpp v28, v28, v28 row_ror:12 row_mask:0xf bank_mask:0x5
	v_add_f32_dpp v29, v29, v29 row_ror:4 row_mask:0xf bank_mask:0xa
	v_add_f32_dpp v22, v22, v22 quad_perm:[1,0,3,2] row_mask:0xf bank_mask:0xf
	v_add_f32_dpp v23, v23, v23 quad_perm:[1,0,3,2] row_mask:0xf bank_mask:0xf
	v_pk_fma_f32 v[84:85], v[72:73], v[80:81], v[84:85] op_sel:[0,0,0] op_sel_hi:[0,1,1]
	v_add_f32_dpp v58, v58, v58 row_ror:12 row_mask:0xf bank_mask:0x5
	v_add_f32_dpp v22, v22, v22 quad_perm:[2,3,0,1] row_mask:0xf bank_mask:0xf
	v_add_f32_dpp v23, v23, v23 quad_perm:[2,3,0,1] row_mask:0xf bank_mask:0xf
	v_pk_fma_f32 v[86:87], v[72:73], v[80:81], v[86:87] op_sel:[1,0,0] op_sel_hi:[1,1,1]
	v_add_f32_dpp v59, v59, v59 row_ror:4 row_mask:0xf bank_mask:0xa
	v_add_f32_dpp v22, v22, v22 row_half_mirror row_mask:0xf bank_mask:0xf
	v_add_f32_dpp v23, v23, v23 row_half_mirror row_mask:0xf bank_mask:0xf
	v_pk_fma_f32 v[88:89], v[74:75], v[80:81], v[88:89] op_sel:[0,0,0] op_sel_hi:[0,1,1]
	v_mov_b32_dpp v28, v29 quad_perm:[0,1,2,3] row_mask:0xf bank_mask:0xa
	v_add_f32_dpp v22, v22, v22 row_mirror row_mask:0xf bank_mask:0xf
	v_add_f32_dpp v23, v23, v23 row_mirror row_mask:0xf bank_mask:0xf
	v_pk_fma_f32 v[90:91], v[74:75], v[80:81], v[90:91] op_sel:[1,0,0] op_sel_hi:[1,1,1]
	v_mov_b32_dpp v58, v59 quad_perm:[0,1,2,3] row_mask:0xf bank_mask:0xa
	v_pk_fma_f32 v[2:3], v[68:69], v[22:23], v[84:85] op_sel:[0,0,0] op_sel_hi:[0,1,1] neg_lo:[1,0,0] neg_hi:[1,0,0]
	v_pk_fma_f32 v[4:5], v[68:69], v[22:23], v[86:87] op_sel:[1,0,0] op_sel_hi:[1,1,1] neg_lo:[1,0,0] neg_hi:[1,0,0]
	v_pk_fma_f32 v[6:7], v[70:71], v[22:23], v[88:89] op_sel:[0,0,0] op_sel_hi:[0,1,1] neg_lo:[1,0,0] neg_hi:[1,0,0]
	v_pk_fma_f32 v[8:9], v[70:71], v[22:23], v[90:91] op_sel:[1,0,0] op_sel_hi:[1,1,1] neg_lo:[1,0,0] neg_hi:[1,0,0]
	s_waitcnt lgkmcnt(0)
	ds_read_b128 v[60:63], v20 offset:5888
	ds_read_b128 v[64:67], v20 offset:14080
	ds_read_b64 v[80:81], v21 offset:46848
	ds_read_b128 v[72:75], v20 offset:30464
	ds_read_b128 v[68:71], v20 offset:22272
	ds_read_b128 v[92:95], v20 offset:38656
	v_pk_mul_f32 v[22:23], v[2:3], v[36:37] op_sel:[0,0] op_sel_hi:[1,0]
	v_pk_mul_f32 v[26:27], v[2:3], v[52:53] op_sel:[0,0] op_sel_hi:[1,0]
	v_pk_mul_f32 v[84:85], v[2:3], v[40:41] op_sel:[0,0] op_sel_hi:[1,0]
	v_pk_fma_f32 v[22:23], v[4:5], v[36:37], v[22:23] op_sel:[0,1,0] op_sel_hi:[1,1,1]
	v_pk_fma_f32 v[26:27], v[4:5], v[52:53], v[26:27] op_sel:[0,1,0] op_sel_hi:[1,1,1]
	v_pk_mul_f32 v[86:87], v[4:5], v[40:41] op_sel:[0,1] op_sel_hi:[1,1]
	v_pk_fma_f32 v[22:23], v[6:7], v[38:39], v[22:23] op_sel:[0,0,0] op_sel_hi:[1,0,1]
	v_pk_fma_f32 v[26:27], v[6:7], v[54:55], v[26:27] op_sel:[0,0,0] op_sel_hi:[1,0,1]
	v_pk_mul_f32 v[88:89], v[6:7], v[42:43] op_sel:[0,0] op_sel_hi:[1,0]
	v_pk_fma_f32 v[22:23], v[8:9], v[38:39], v[22:23] op_sel:[0,1,0] op_sel_hi:[1,1,1]
	v_pk_fma_f32 v[26:27], v[8:9], v[54:55], v[26:27] op_sel:[0,1,0] op_sel_hi:[1,1,1]
	v_pk_mul_f32 v[90:91], v[8:9], v[42:43] op_sel:[0,1] op_sel_hi:[1,1]
	v_add_f32_dpp v28, v28, v28 row_ror:8 row_mask:0xf bank_mask:0x3
	v_add_f32_dpp v58, v58, v58 row_ror:8 row_mask:0xf bank_mask:0xc
	v_add_f32_dpp v22, v22, v22 quad_perm:[1,0,3,2] row_mask:0xf bank_mask:0xf
	v_add_f32_dpp v23, v23, v23 quad_perm:[1,0,3,2] row_mask:0xf bank_mask:0xf
	v_pk_fma_f32 v[84:85], v[48:49], v[56:57], v[84:85] op_sel:[0,0,0] op_sel_hi:[0,1,1]
	v_mov_b32_dpp v28, v58 quad_perm:[0,1,2,3] row_mask:0xf bank_mask:0xc
	v_add_f32_dpp v22, v22, v22 quad_perm:[2,3,0,1] row_mask:0xf bank_mask:0xf
	v_add_f32_dpp v23, v23, v23 quad_perm:[2,3,0,1] row_mask:0xf bank_mask:0xf
	v_pk_fma_f32 v[86:87], v[48:49], v[56:57], v[86:87] op_sel:[1,0,0] op_sel_hi:[1,1,1]
	v_add_f32_dpp v28, v28, v28 quad_perm:[1,0,3,2] row_mask:0xf bank_mask:0xf
	v_add_f32_dpp v22, v22, v22 row_half_mirror row_mask:0xf bank_mask:0xf
	v_add_f32_dpp v23, v23, v23 row_half_mirror row_mask:0xf bank_mask:0xf
	v_pk_fma_f32 v[88:89], v[50:51], v[56:57], v[88:89] op_sel:[0,0,0] op_sel_hi:[0,1,1]
	v_add_f32_dpp v28, v28, v28 quad_perm:[2,3,0,1] row_mask:0xf bank_mask:0xf
	v_add_f32_dpp v22, v22, v22 row_mirror row_mask:0xf bank_mask:0xf
	v_add_f32_dpp v23, v23, v23 row_mirror row_mask:0xf bank_mask:0xf
	v_pk_fma_f32 v[90:91], v[50:51], v[56:57], v[90:91] op_sel:[1,0,0] op_sel_hi:[1,1,1]
	v_cndmask_b32_e64 v32, v32, v28, s[6:7]
	v_pk_fma_f32 v[2:3], v[44:45], v[22:23], v[84:85] op_sel:[0,0,0] op_sel_hi:[0,1,1] neg_lo:[1,0,0] neg_hi:[1,0,0]
	v_pk_fma_f32 v[4:5], v[44:45], v[22:23], v[86:87] op_sel:[1,0,0] op_sel_hi:[1,1,1] neg_lo:[1,0,0] neg_hi:[1,0,0]
	v_pk_fma_f32 v[6:7], v[46:47], v[22:23], v[88:89] op_sel:[0,0,0] op_sel_hi:[0,1,1] neg_lo:[1,0,0] neg_hi:[1,0,0]
	v_pk_fma_f32 v[8:9], v[46:47], v[22:23], v[90:91] op_sel:[1,0,0] op_sel_hi:[1,1,1] neg_lo:[1,0,0] neg_hi:[1,0,0]
	s_waitcnt lgkmcnt(0)
	ds_read_b128 v[36:39], v20 offset:6144
	ds_read_b128 v[40:43], v20 offset:14336
	ds_read_b64 v[56:57], v21 offset:47104
	ds_read_b128 v[48:51], v20 offset:30720
	ds_read_b128 v[44:47], v20 offset:22528
	ds_read_b128 v[52:55], v20 offset:38912
	v_pk_mul_f32 v[22:23], v[2:3], v[60:61] op_sel:[0,0] op_sel_hi:[1,0]
	v_pk_mul_f32 v[28:29], v[2:3], v[76:77] op_sel:[0,0] op_sel_hi:[1,0]
	v_pk_mul_f32 v[84:85], v[2:3], v[64:65] op_sel:[0,0] op_sel_hi:[1,0]
	v_pk_fma_f32 v[22:23], v[4:5], v[60:61], v[22:23] op_sel:[0,1,0] op_sel_hi:[1,1,1]
	v_pk_fma_f32 v[28:29], v[4:5], v[76:77], v[28:29] op_sel:[0,1,0] op_sel_hi:[1,1,1]
	v_pk_mul_f32 v[86:87], v[4:5], v[64:65] op_sel:[0,1] op_sel_hi:[1,1]
	v_pk_fma_f32 v[22:23], v[6:7], v[62:63], v[22:23] op_sel:[0,0,0] op_sel_hi:[1,0,1]
	v_pk_fma_f32 v[28:29], v[6:7], v[78:79], v[28:29] op_sel:[0,0,0] op_sel_hi:[1,0,1]
	v_pk_mul_f32 v[88:89], v[6:7], v[66:67] op_sel:[0,0] op_sel_hi:[1,0]
	v_pk_fma_f32 v[22:23], v[8:9], v[62:63], v[22:23] op_sel:[0,1,0] op_sel_hi:[1,1,1]
	v_pk_fma_f32 v[28:29], v[8:9], v[78:79], v[28:29] op_sel:[0,1,0] op_sel_hi:[1,1,1]
	v_pk_mul_f32 v[90:91], v[8:9], v[66:67] op_sel:[0,1] op_sel_hi:[1,1]
	v_add_f32_dpp v24, v24, v24 row_ror:12 row_mask:0xf bank_mask:0x5
	v_add_f32_dpp v25, v25, v25 row_ror:4 row_mask:0xf bank_mask:0xa
	v_add_f32_dpp v22, v22, v22 quad_perm:[1,0,3,2] row_mask:0xf bank_mask:0xf
	v_add_f32_dpp v23, v23, v23 quad_perm:[1,0,3,2] row_mask:0xf bank_mask:0xf
	v_pk_fma_f32 v[84:85], v[72:73], v[80:81], v[84:85] op_sel:[0,0,0] op_sel_hi:[0,1,1]
	v_add_f32_dpp v26, v26, v26 row_ror:12 row_mask:0xf bank_mask:0x5
	v_add_f32_dpp v22, v22, v22 quad_perm:[2,3,0,1] row_mask:0xf bank_mask:0xf
	v_add_f32_dpp v23, v23, v23 quad_perm:[2,3,0,1] row_mask:0xf bank_mask:0xf
	v_pk_fma_f32 v[86:87], v[72:73], v[80:81], v[86:87] op_sel:[1,0,0] op_sel_hi:[1,1,1]
	v_add_f32_dpp v27, v27, v27 row_ror:4 row_mask:0xf bank_mask:0xa
	v_add_f32_dpp v22, v22, v22 row_half_mirror row_mask:0xf bank_mask:0xf
	v_add_f32_dpp v23, v23, v23 row_half_mirror row_mask:0xf bank_mask:0xf
	v_pk_fma_f32 v[88:89], v[74:75], v[80:81], v[88:89] op_sel:[0,0,0] op_sel_hi:[0,1,1]
	v_mov_b32_dpp v24, v25 quad_perm:[0,1,2,3] row_mask:0xf bank_mask:0xa
	v_add_f32_dpp v22, v22, v22 row_mirror row_mask:0xf bank_mask:0xf
	v_add_f32_dpp v23, v23, v23 row_mirror row_mask:0xf bank_mask:0xf
	v_pk_fma_f32 v[90:91], v[74:75], v[80:81], v[90:91] op_sel:[1,0,0] op_sel_hi:[1,1,1]
	v_mov_b32_dpp v26, v27 quad_perm:[0,1,2,3] row_mask:0xf bank_mask:0xa
	v_pk_fma_f32 v[2:3], v[68:69], v[22:23], v[84:85] op_sel:[0,0,0] op_sel_hi:[0,1,1] neg_lo:[1,0,0] neg_hi:[1,0,0]
	v_pk_fma_f32 v[4:5], v[68:69], v[22:23], v[86:87] op_sel:[1,0,0] op_sel_hi:[1,1,1] neg_lo:[1,0,0] neg_hi:[1,0,0]
	v_pk_fma_f32 v[6:7], v[70:71], v[22:23], v[88:89] op_sel:[0,0,0] op_sel_hi:[0,1,1] neg_lo:[1,0,0] neg_hi:[1,0,0]
	v_pk_fma_f32 v[8:9], v[70:71], v[22:23], v[90:91] op_sel:[1,0,0] op_sel_hi:[1,1,1] neg_lo:[1,0,0] neg_hi:[1,0,0]
	s_waitcnt lgkmcnt(0)
	ds_read_b128 v[60:63], v20 offset:6400
	ds_read_b128 v[64:67], v20 offset:14592
	ds_read_b64 v[80:81], v21 offset:47360
	ds_read_b128 v[72:75], v20 offset:30976
	ds_read_b128 v[68:71], v20 offset:22784
	ds_read_b128 v[76:79], v20 offset:39168
	v_pk_mul_f32 v[22:23], v[2:3], v[36:37] op_sel:[0,0] op_sel_hi:[1,0]
	v_pk_mul_f32 v[58:59], v[2:3], v[92:93] op_sel:[0,0] op_sel_hi:[1,0]
	v_pk_mul_f32 v[84:85], v[2:3], v[40:41] op_sel:[0,0] op_sel_hi:[1,0]
	v_pk_fma_f32 v[22:23], v[4:5], v[36:37], v[22:23] op_sel:[0,1,0] op_sel_hi:[1,1,1]
	v_pk_fma_f32 v[58:59], v[4:5], v[92:93], v[58:59] op_sel:[0,1,0] op_sel_hi:[1,1,1]
	v_pk_mul_f32 v[86:87], v[4:5], v[40:41] op_sel:[0,1] op_sel_hi:[1,1]
	v_pk_fma_f32 v[22:23], v[6:7], v[38:39], v[22:23] op_sel:[0,0,0] op_sel_hi:[1,0,1]
	v_pk_fma_f32 v[58:59], v[6:7], v[94:95], v[58:59] op_sel:[0,0,0] op_sel_hi:[1,0,1]
	v_pk_mul_f32 v[88:89], v[6:7], v[42:43] op_sel:[0,0] op_sel_hi:[1,0]
	v_pk_fma_f32 v[22:23], v[8:9], v[38:39], v[22:23] op_sel:[0,1,0] op_sel_hi:[1,1,1]
	v_pk_fma_f32 v[58:59], v[8:9], v[94:95], v[58:59] op_sel:[0,1,0] op_sel_hi:[1,1,1]
	v_pk_mul_f32 v[90:91], v[8:9], v[42:43] op_sel:[0,1] op_sel_hi:[1,1]
	v_add_f32_dpp v24, v24, v24 row_ror:8 row_mask:0xf bank_mask:0x3
	v_add_f32_dpp v26, v26, v26 row_ror:8 row_mask:0xf bank_mask:0xc
	v_add_f32_dpp v22, v22, v22 quad_perm:[1,0,3,2] row_mask:0xf bank_mask:0xf
	v_add_f32_dpp v23, v23, v23 quad_perm:[1,0,3,2] row_mask:0xf bank_mask:0xf
	v_pk_fma_f32 v[84:85], v[48:49], v[56:57], v[84:85] op_sel:[0,0,0] op_sel_hi:[0,1,1]
	v_mov_b32_dpp v24, v26 quad_perm:[0,1,2,3] row_mask:0xf bank_mask:0xc
	v_add_f32_dpp v22, v22, v22 quad_perm:[2,3,0,1] row_mask:0xf bank_mask:0xf
	v_add_f32_dpp v23, v23, v23 quad_perm:[2,3,0,1] row_mask:0xf bank_mask:0xf
	v_pk_fma_f32 v[86:87], v[48:49], v[56:57], v[86:87] op_sel:[1,0,0] op_sel_hi:[1,1,1]
	v_add_f32_dpp v24, v24, v24 quad_perm:[1,0,3,2] row_mask:0xf bank_mask:0xf
	v_add_f32_dpp v22, v22, v22 row_half_mirror row_mask:0xf bank_mask:0xf
	v_add_f32_dpp v23, v23, v23 row_half_mirror row_mask:0xf bank_mask:0xf
	v_pk_fma_f32 v[88:89], v[50:51], v[56:57], v[88:89] op_sel:[0,0,0] op_sel_hi:[0,1,1]
	v_add_f32_dpp v24, v24, v24 quad_perm:[2,3,0,1] row_mask:0xf bank_mask:0xf
	v_add_f32_dpp v22, v22, v22 row_mirror row_mask:0xf bank_mask:0xf
	v_add_f32_dpp v23, v23, v23 row_mirror row_mask:0xf bank_mask:0xf
	v_pk_fma_f32 v[90:91], v[50:51], v[56:57], v[90:91] op_sel:[1,0,0] op_sel_hi:[1,1,1]
	v_cndmask_b32_e64 v32, v32, v24, s[8:9]
	v_pk_fma_f32 v[2:3], v[44:45], v[22:23], v[84:85] op_sel:[0,0,0] op_sel_hi:[0,1,1] neg_lo:[1,0,0] neg_hi:[1,0,0]
	v_pk_fma_f32 v[4:5], v[44:45], v[22:23], v[86:87] op_sel:[1,0,0] op_sel_hi:[1,1,1] neg_lo:[1,0,0] neg_hi:[1,0,0]
	v_pk_fma_f32 v[6:7], v[46:47], v[22:23], v[88:89] op_sel:[0,0,0] op_sel_hi:[0,1,1] neg_lo:[1,0,0] neg_hi:[1,0,0]
	v_pk_fma_f32 v[8:9], v[46:47], v[22:23], v[90:91] op_sel:[1,0,0] op_sel_hi:[1,1,1] neg_lo:[1,0,0] neg_hi:[1,0,0]
	s_waitcnt lgkmcnt(0)
	ds_read_b128 v[36:39], v20 offset:6656
	ds_read_b128 v[40:43], v20 offset:14848
	ds_read_b64 v[56:57], v21 offset:47616
	ds_read_b128 v[48:51], v20 offset:31232
	ds_read_b128 v[44:47], v20 offset:23040
	ds_read_b128 v[92:95], v20 offset:39424
	v_pk_mul_f32 v[22:23], v[2:3], v[60:61] op_sel:[0,0] op_sel_hi:[1,0]
	v_pk_mul_f32 v[24:25], v[2:3], v[52:53] op_sel:[0,0] op_sel_hi:[1,0]
	v_pk_mul_f32 v[84:85], v[2:3], v[64:65] op_sel:[0,0] op_sel_hi:[1,0]
	v_pk_fma_f32 v[22:23], v[4:5], v[60:61], v[22:23] op_sel:[0,1,0] op_sel_hi:[1,1,1]
	v_pk_fma_f32 v[24:25], v[4:5], v[52:53], v[24:25] op_sel:[0,1,0] op_sel_hi:[1,1,1]
	v_pk_mul_f32 v[86:87], v[4:5], v[64:65] op_sel:[0,1] op_sel_hi:[1,1]
	v_pk_fma_f32 v[22:23], v[6:7], v[62:63], v[22:23] op_sel:[0,0,0] op_sel_hi:[1,0,1]
	v_pk_fma_f32 v[24:25], v[6:7], v[54:55], v[24:25] op_sel:[0,0,0] op_sel_hi:[1,0,1]
	v_pk_mul_f32 v[88:89], v[6:7], v[66:67] op_sel:[0,0] op_sel_hi:[1,0]
	v_pk_fma_f32 v[22:23], v[8:9], v[62:63], v[22:23] op_sel:[0,1,0] op_sel_hi:[1,1,1]
	v_pk_fma_f32 v[24:25], v[8:9], v[54:55], v[24:25] op_sel:[0,1,0] op_sel_hi:[1,1,1]
	v_pk_mul_f32 v[90:91], v[8:9], v[66:67] op_sel:[0,1] op_sel_hi:[1,1]
	v_add_f32_dpp v28, v28, v28 row_ror:12 row_mask:0xf bank_mask:0x5
	v_add_f32_dpp v29, v29, v29 row_ror:4 row_mask:0xf bank_mask:0xa
	v_add_f32_dpp v22, v22, v22 quad_perm:[1,0,3,2] row_mask:0xf bank_mask:0xf
	v_add_f32_dpp v23, v23, v23 quad_perm:[1,0,3,2] row_mask:0xf bank_mask:0xf
	v_pk_fma_f32 v[84:85], v[72:73], v[80:81], v[84:85] op_sel:[0,0,0] op_sel_hi:[0,1,1]
	v_add_f32_dpp v58, v58, v58 row_ror:12 row_mask:0xf bank_mask:0x5
	v_add_f32_dpp v22, v22, v22 quad_perm:[2,3,0,1] row_mask:0xf bank_mask:0xf
	v_add_f32_dpp v23, v23, v23 quad_perm:[2,3,0,1] row_mask:0xf bank_mask:0xf
	v_pk_fma_f32 v[86:87], v[72:73], v[80:81], v[86:87] op_sel:[1,0,0] op_sel_hi:[1,1,1]
	v_add_f32_dpp v59, v59, v59 row_ror:4 row_mask:0xf bank_mask:0xa
	v_add_f32_dpp v22, v22, v22 row_half_mirror row_mask:0xf bank_mask:0xf
	v_add_f32_dpp v23, v23, v23 row_half_mirror row_mask:0xf bank_mask:0xf
	v_pk_fma_f32 v[88:89], v[74:75], v[80:81], v[88:89] op_sel:[0,0,0] op_sel_hi:[0,1,1]
	v_mov_b32_dpp v28, v29 quad_perm:[0,1,2,3] row_mask:0xf bank_mask:0xa
	v_add_f32_dpp v22, v22, v22 row_mirror row_mask:0xf bank_mask:0xf
	v_add_f32_dpp v23, v23, v23 row_mirror row_mask:0xf bank_mask:0xf
	v_pk_fma_f32 v[90:91], v[74:75], v[80:81], v[90:91] op_sel:[1,0,0] op_sel_hi:[1,1,1]
	v_mov_b32_dpp v58, v59 quad_perm:[0,1,2,3] row_mask:0xf bank_mask:0xa
	v_pk_fma_f32 v[2:3], v[68:69], v[22:23], v[84:85] op_sel:[0,0,0] op_sel_hi:[0,1,1] neg_lo:[1,0,0] neg_hi:[1,0,0]
	v_pk_fma_f32 v[4:5], v[68:69], v[22:23], v[86:87] op_sel:[1,0,0] op_sel_hi:[1,1,1] neg_lo:[1,0,0] neg_hi:[1,0,0]
	v_pk_fma_f32 v[6:7], v[70:71], v[22:23], v[88:89] op_sel:[0,0,0] op_sel_hi:[0,1,1] neg_lo:[1,0,0] neg_hi:[1,0,0]
	v_pk_fma_f32 v[8:9], v[70:71], v[22:23], v[90:91] op_sel:[1,0,0] op_sel_hi:[1,1,1] neg_lo:[1,0,0] neg_hi:[1,0,0]
	s_waitcnt lgkmcnt(0)
	ds_read_b128 v[60:63], v20 offset:6912
	ds_read_b128 v[64:67], v20 offset:15104
	ds_read_b64 v[80:81], v21 offset:47872
	ds_read_b128 v[72:75], v20 offset:31488
	ds_read_b128 v[68:71], v20 offset:23296
	ds_read_b128 v[52:55], v20 offset:39680
	v_pk_mul_f32 v[22:23], v[2:3], v[36:37] op_sel:[0,0] op_sel_hi:[1,0]
	v_pk_mul_f32 v[26:27], v[2:3], v[76:77] op_sel:[0,0] op_sel_hi:[1,0]
	v_pk_mul_f32 v[84:85], v[2:3], v[40:41] op_sel:[0,0] op_sel_hi:[1,0]
	v_pk_fma_f32 v[22:23], v[4:5], v[36:37], v[22:23] op_sel:[0,1,0] op_sel_hi:[1,1,1]
	v_pk_fma_f32 v[26:27], v[4:5], v[76:77], v[26:27] op_sel:[0,1,0] op_sel_hi:[1,1,1]
	v_pk_mul_f32 v[86:87], v[4:5], v[40:41] op_sel:[0,1] op_sel_hi:[1,1]
	v_pk_fma_f32 v[22:23], v[6:7], v[38:39], v[22:23] op_sel:[0,0,0] op_sel_hi:[1,0,1]
	v_pk_fma_f32 v[26:27], v[6:7], v[78:79], v[26:27] op_sel:[0,0,0] op_sel_hi:[1,0,1]
	v_pk_mul_f32 v[88:89], v[6:7], v[42:43] op_sel:[0,0] op_sel_hi:[1,0]
	v_pk_fma_f32 v[22:23], v[8:9], v[38:39], v[22:23] op_sel:[0,1,0] op_sel_hi:[1,1,1]
	v_pk_fma_f32 v[26:27], v[8:9], v[78:79], v[26:27] op_sel:[0,1,0] op_sel_hi:[1,1,1]
	v_pk_mul_f32 v[90:91], v[8:9], v[42:43] op_sel:[0,1] op_sel_hi:[1,1]
	v_add_f32_dpp v28, v28, v28 row_ror:8 row_mask:0xf bank_mask:0x3
	v_add_f32_dpp v58, v58, v58 row_ror:8 row_mask:0xf bank_mask:0xc
	v_add_f32_dpp v22, v22, v22 quad_perm:[1,0,3,2] row_mask:0xf bank_mask:0xf
	v_add_f32_dpp v23, v23, v23 quad_perm:[1,0,3,2] row_mask:0xf bank_mask:0xf
	v_pk_fma_f32 v[84:85], v[48:49], v[56:57], v[84:85] op_sel:[0,0,0] op_sel_hi:[0,1,1]
	v_mov_b32_dpp v28, v58 quad_perm:[0,1,2,3] row_mask:0xf bank_mask:0xc
	v_add_f32_dpp v22, v22, v22 quad_perm:[2,3,0,1] row_mask:0xf bank_mask:0xf
	v_add_f32_dpp v23, v23, v23 quad_perm:[2,3,0,1] row_mask:0xf bank_mask:0xf
	v_pk_fma_f32 v[86:87], v[48:49], v[56:57], v[86:87] op_sel:[1,0,0] op_sel_hi:[1,1,1]
	v_add_f32_dpp v28, v28, v28 quad_perm:[1,0,3,2] row_mask:0xf bank_mask:0xf
	v_add_f32_dpp v22, v22, v22 row_half_mirror row_mask:0xf bank_mask:0xf
	v_add_f32_dpp v23, v23, v23 row_half_mirror row_mask:0xf bank_mask:0xf
	v_pk_fma_f32 v[88:89], v[50:51], v[56:57], v[88:89] op_sel:[0,0,0] op_sel_hi:[0,1,1]
	v_add_f32_dpp v28, v28, v28 quad_perm:[2,3,0,1] row_mask:0xf bank_mask:0xf
	v_add_f32_dpp v22, v22, v22 row_mirror row_mask:0xf bank_mask:0xf
	v_add_f32_dpp v23, v23, v23 row_mirror row_mask:0xf bank_mask:0xf
	v_pk_fma_f32 v[90:91], v[50:51], v[56:57], v[90:91] op_sel:[1,0,0] op_sel_hi:[1,1,1]
	v_cndmask_b32_e64 v32, v32, v28, s[10:11]
	v_pk_fma_f32 v[2:3], v[44:45], v[22:23], v[84:85] op_sel:[0,0,0] op_sel_hi:[0,1,1] neg_lo:[1,0,0] neg_hi:[1,0,0]
	v_pk_fma_f32 v[4:5], v[44:45], v[22:23], v[86:87] op_sel:[1,0,0] op_sel_hi:[1,1,1] neg_lo:[1,0,0] neg_hi:[1,0,0]
	v_pk_fma_f32 v[6:7], v[46:47], v[22:23], v[88:89] op_sel:[0,0,0] op_sel_hi:[0,1,1] neg_lo:[1,0,0] neg_hi:[1,0,0]
	v_pk_fma_f32 v[8:9], v[46:47], v[22:23], v[90:91] op_sel:[1,0,0] op_sel_hi:[1,1,1] neg_lo:[1,0,0] neg_hi:[1,0,0]
	s_waitcnt lgkmcnt(0)
	ds_read_b128 v[36:39], v20 offset:7168
	ds_read_b128 v[40:43], v20 offset:15360
	ds_read_b64 v[56:57], v21 offset:48128
	ds_read_b128 v[48:51], v20 offset:31744
	ds_read_b128 v[44:47], v20 offset:23552
	ds_read_b128 v[76:79], v20 offset:39936
	v_pk_mul_f32 v[22:23], v[2:3], v[60:61] op_sel:[0,0] op_sel_hi:[1,0]
	v_pk_mul_f32 v[28:29], v[2:3], v[92:93] op_sel:[0,0] op_sel_hi:[1,0]
	v_pk_mul_f32 v[84:85], v[2:3], v[64:65] op_sel:[0,0] op_sel_hi:[1,0]
	v_pk_fma_f32 v[22:23], v[4:5], v[60:61], v[22:23] op_sel:[0,1,0] op_sel_hi:[1,1,1]
	v_pk_fma_f32 v[28:29], v[4:5], v[92:93], v[28:29] op_sel:[0,1,0] op_sel_hi:[1,1,1]
	v_pk_mul_f32 v[86:87], v[4:5], v[64:65] op_sel:[0,1] op_sel_hi:[1,1]
	v_pk_fma_f32 v[22:23], v[6:7], v[62:63], v[22:23] op_sel:[0,0,0] op_sel_hi:[1,0,1]
	v_pk_fma_f32 v[28:29], v[6:7], v[94:95], v[28:29] op_sel:[0,0,0] op_sel_hi:[1,0,1]
	v_pk_mul_f32 v[88:89], v[6:7], v[66:67] op_sel:[0,0] op_sel_hi:[1,0]
	v_pk_fma_f32 v[22:23], v[8:9], v[62:63], v[22:23] op_sel:[0,1,0] op_sel_hi:[1,1,1]
	v_pk_fma_f32 v[28:29], v[8:9], v[94:95], v[28:29] op_sel:[0,1,0] op_sel_hi:[1,1,1]
	v_pk_mul_f32 v[90:91], v[8:9], v[66:67] op_sel:[0,1] op_sel_hi:[1,1]
	v_add_f32_dpp v24, v24, v24 row_ror:12 row_mask:0xf bank_mask:0x5
	v_add_f32_dpp v25, v25, v25 row_ror:4 row_mask:0xf bank_mask:0xa
	v_add_f32_dpp v22, v22, v22 quad_perm:[1,0,3,2] row_mask:0xf bank_mask:0xf
	v_add_f32_dpp v23, v23, v23 quad_perm:[1,0,3,2] row_mask:0xf bank_mask:0xf
	v_pk_fma_f32 v[84:85], v[72:73], v[80:81], v[84:85] op_sel:[0,0,0] op_sel_hi:[0,1,1]
	v_add_f32_dpp v26, v26, v26 row_ror:12 row_mask:0xf bank_mask:0x5
	v_add_f32_dpp v22, v22, v22 quad_perm:[2,3,0,1] row_mask:0xf bank_mask:0xf
	v_add_f32_dpp v23, v23, v23 quad_perm:[2,3,0,1] row_mask:0xf bank_mask:0xf
	v_pk_fma_f32 v[86:87], v[72:73], v[80:81], v[86:87] op_sel:[1,0,0] op_sel_hi:[1,1,1]
	v_add_f32_dpp v27, v27, v27 row_ror:4 row_mask:0xf bank_mask:0xa
	v_add_f32_dpp v22, v22, v22 row_half_mirror row_mask:0xf bank_mask:0xf
	v_add_f32_dpp v23, v23, v23 row_half_mirror row_mask:0xf bank_mask:0xf
	v_pk_fma_f32 v[88:89], v[74:75], v[80:81], v[88:89] op_sel:[0,0,0] op_sel_hi:[0,1,1]
	v_mov_b32_dpp v24, v25 quad_perm:[0,1,2,3] row_mask:0xf bank_mask:0xa
	v_add_f32_dpp v22, v22, v22 row_mirror row_mask:0xf bank_mask:0xf
	v_add_f32_dpp v23, v23, v23 row_mirror row_mask:0xf bank_mask:0xf
	v_pk_fma_f32 v[90:91], v[74:75], v[80:81], v[90:91] op_sel:[1,0,0] op_sel_hi:[1,1,1]
	v_mov_b32_dpp v26, v27 quad_perm:[0,1,2,3] row_mask:0xf bank_mask:0xa
	v_pk_fma_f32 v[2:3], v[68:69], v[22:23], v[84:85] op_sel:[0,0,0] op_sel_hi:[0,1,1] neg_lo:[1,0,0] neg_hi:[1,0,0]
	v_pk_fma_f32 v[4:5], v[68:69], v[22:23], v[86:87] op_sel:[1,0,0] op_sel_hi:[1,1,1] neg_lo:[1,0,0] neg_hi:[1,0,0]
	v_pk_fma_f32 v[6:7], v[70:71], v[22:23], v[88:89] op_sel:[0,0,0] op_sel_hi:[0,1,1] neg_lo:[1,0,0] neg_hi:[1,0,0]
	v_pk_fma_f32 v[8:9], v[70:71], v[22:23], v[90:91] op_sel:[1,0,0] op_sel_hi:[1,1,1] neg_lo:[1,0,0] neg_hi:[1,0,0]
	s_waitcnt lgkmcnt(0)
	ds_read_b128 v[60:63], v20 offset:7424
	ds_read_b128 v[64:67], v20 offset:15616
	ds_read_b64 v[80:81], v21 offset:48384
	ds_read_b128 v[72:75], v20 offset:32000
	ds_read_b128 v[68:71], v20 offset:23808
	ds_read_b128 v[92:95], v20 offset:40192
	v_pk_mul_f32 v[22:23], v[2:3], v[36:37] op_sel:[0,0] op_sel_hi:[1,0]
	v_pk_mul_f32 v[58:59], v[2:3], v[52:53] op_sel:[0,0] op_sel_hi:[1,0]
	v_pk_mul_f32 v[84:85], v[2:3], v[40:41] op_sel:[0,0] op_sel_hi:[1,0]
	v_pk_fma_f32 v[22:23], v[4:5], v[36:37], v[22:23] op_sel:[0,1,0] op_sel_hi:[1,1,1]
	v_pk_fma_f32 v[58:59], v[4:5], v[52:53], v[58:59] op_sel:[0,1,0] op_sel_hi:[1,1,1]
	v_pk_mul_f32 v[86:87], v[4:5], v[40:41] op_sel:[0,1] op_sel_hi:[1,1]
	v_pk_fma_f32 v[22:23], v[6:7], v[38:39], v[22:23] op_sel:[0,0,0] op_sel_hi:[1,0,1]
	v_pk_fma_f32 v[58:59], v[6:7], v[54:55], v[58:59] op_sel:[0,0,0] op_sel_hi:[1,0,1]
	v_pk_mul_f32 v[88:89], v[6:7], v[42:43] op_sel:[0,0] op_sel_hi:[1,0]
	v_pk_fma_f32 v[22:23], v[8:9], v[38:39], v[22:23] op_sel:[0,1,0] op_sel_hi:[1,1,1]
	v_pk_fma_f32 v[58:59], v[8:9], v[54:55], v[58:59] op_sel:[0,1,0] op_sel_hi:[1,1,1]
	v_pk_mul_f32 v[90:91], v[8:9], v[42:43] op_sel:[0,1] op_sel_hi:[1,1]
	v_add_f32_dpp v24, v24, v24 row_ror:8 row_mask:0xf bank_mask:0x3
	v_add_f32_dpp v26, v26, v26 row_ror:8 row_mask:0xf bank_mask:0xc
	v_add_f32_dpp v22, v22, v22 quad_perm:[1,0,3,2] row_mask:0xf bank_mask:0xf
	v_add_f32_dpp v23, v23, v23 quad_perm:[1,0,3,2] row_mask:0xf bank_mask:0xf
	v_pk_fma_f32 v[84:85], v[48:49], v[56:57], v[84:85] op_sel:[0,0,0] op_sel_hi:[0,1,1]
	v_mov_b32_dpp v24, v26 quad_perm:[0,1,2,3] row_mask:0xf bank_mask:0xc
	v_add_f32_dpp v22, v22, v22 quad_perm:[2,3,0,1] row_mask:0xf bank_mask:0xf
	v_add_f32_dpp v23, v23, v23 quad_perm:[2,3,0,1] row_mask:0xf bank_mask:0xf
	v_pk_fma_f32 v[86:87], v[48:49], v[56:57], v[86:87] op_sel:[1,0,0] op_sel_hi:[1,1,1]
	v_add_f32_dpp v24, v24, v24 quad_perm:[1,0,3,2] row_mask:0xf bank_mask:0xf
	v_add_f32_dpp v22, v22, v22 row_half_mirror row_mask:0xf bank_mask:0xf
	v_add_f32_dpp v23, v23, v23 row_half_mirror row_mask:0xf bank_mask:0xf
	v_pk_fma_f32 v[88:89], v[50:51], v[56:57], v[88:89] op_sel:[0,0,0] op_sel_hi:[0,1,1]
	v_add_f32_dpp v24, v24, v24 quad_perm:[2,3,0,1] row_mask:0xf bank_mask:0xf
	v_add_f32_dpp v22, v22, v22 row_mirror row_mask:0xf bank_mask:0xf
	v_add_f32_dpp v23, v23, v23 row_mirror row_mask:0xf bank_mask:0xf
	v_pk_fma_f32 v[90:91], v[50:51], v[56:57], v[90:91] op_sel:[1,0,0] op_sel_hi:[1,1,1]
	v_cndmask_b32_e64 v33, 0, v24, s[0:1]
	v_pk_fma_f32 v[2:3], v[44:45], v[22:23], v[84:85] op_sel:[0,0,0] op_sel_hi:[0,1,1] neg_lo:[1,0,0] neg_hi:[1,0,0]
	v_pk_fma_f32 v[4:5], v[44:45], v[22:23], v[86:87] op_sel:[1,0,0] op_sel_hi:[1,1,1] neg_lo:[1,0,0] neg_hi:[1,0,0]
	v_pk_fma_f32 v[6:7], v[46:47], v[22:23], v[88:89] op_sel:[0,0,0] op_sel_hi:[0,1,1] neg_lo:[1,0,0] neg_hi:[1,0,0]
	v_pk_fma_f32 v[8:9], v[46:47], v[22:23], v[90:91] op_sel:[1,0,0] op_sel_hi:[1,1,1] neg_lo:[1,0,0] neg_hi:[1,0,0]
	s_waitcnt lgkmcnt(0)
	ds_read_b128 v[36:39], v20 offset:7680
	ds_read_b128 v[40:43], v20 offset:15872
	ds_read_b64 v[56:57], v21 offset:48640
	ds_read_b128 v[48:51], v20 offset:32256
	ds_read_b128 v[44:47], v20 offset:24064
	ds_read_b128 v[52:55], v20 offset:40448
	v_pk_mul_f32 v[22:23], v[2:3], v[60:61] op_sel:[0,0] op_sel_hi:[1,0]
	v_pk_mul_f32 v[24:25], v[2:3], v[76:77] op_sel:[0,0] op_sel_hi:[1,0]
	v_pk_mul_f32 v[84:85], v[2:3], v[64:65] op_sel:[0,0] op_sel_hi:[1,0]
	v_pk_fma_f32 v[22:23], v[4:5], v[60:61], v[22:23] op_sel:[0,1,0] op_sel_hi:[1,1,1]
	v_pk_fma_f32 v[24:25], v[4:5], v[76:77], v[24:25] op_sel:[0,1,0] op_sel_hi:[1,1,1]
	v_pk_mul_f32 v[86:87], v[4:5], v[64:65] op_sel:[0,1] op_sel_hi:[1,1]
	v_pk_fma_f32 v[22:23], v[6:7], v[62:63], v[22:23] op_sel:[0,0,0] op_sel_hi:[1,0,1]
	v_pk_fma_f32 v[24:25], v[6:7], v[78:79], v[24:25] op_sel:[0,0,0] op_sel_hi:[1,0,1]
	v_pk_mul_f32 v[88:89], v[6:7], v[66:67] op_sel:[0,0] op_sel_hi:[1,0]
	v_pk_fma_f32 v[22:23], v[8:9], v[62:63], v[22:23] op_sel:[0,1,0] op_sel_hi:[1,1,1]
	v_pk_fma_f32 v[24:25], v[8:9], v[78:79], v[24:25] op_sel:[0,1,0] op_sel_hi:[1,1,1]
	v_pk_mul_f32 v[90:91], v[8:9], v[66:67] op_sel:[0,1] op_sel_hi:[1,1]
	v_add_f32_dpp v28, v28, v28 row_ror:12 row_mask:0xf bank_mask:0x5
	v_add_f32_dpp v29, v29, v29 row_ror:4 row_mask:0xf bank_mask:0xa
	v_add_f32_dpp v22, v22, v22 quad_perm:[1,0,3,2] row_mask:0xf bank_mask:0xf
	v_add_f32_dpp v23, v23, v23 quad_perm:[1,0,3,2] row_mask:0xf bank_mask:0xf
	v_pk_fma_f32 v[84:85], v[72:73], v[80:81], v[84:85] op_sel:[0,0,0] op_sel_hi:[0,1,1]
	v_add_f32_dpp v58, v58, v58 row_ror:12 row_mask:0xf bank_mask:0x5
	v_add_f32_dpp v22, v22, v22 quad_perm:[2,3,0,1] row_mask:0xf bank_mask:0xf
	v_add_f32_dpp v23, v23, v23 quad_perm:[2,3,0,1] row_mask:0xf bank_mask:0xf
	v_pk_fma_f32 v[86:87], v[72:73], v[80:81], v[86:87] op_sel:[1,0,0] op_sel_hi:[1,1,1]
	v_add_f32_dpp v59, v59, v59 row_ror:4 row_mask:0xf bank_mask:0xa
	v_add_f32_dpp v22, v22, v22 row_half_mirror row_mask:0xf bank_mask:0xf
	v_add_f32_dpp v23, v23, v23 row_half_mirror row_mask:0xf bank_mask:0xf
	v_pk_fma_f32 v[88:89], v[74:75], v[80:81], v[88:89] op_sel:[0,0,0] op_sel_hi:[0,1,1]
	v_mov_b32_dpp v28, v29 quad_perm:[0,1,2,3] row_mask:0xf bank_mask:0xa
	v_add_f32_dpp v22, v22, v22 row_mirror row_mask:0xf bank_mask:0xf
	v_add_f32_dpp v23, v23, v23 row_mirror row_mask:0xf bank_mask:0xf
	v_pk_fma_f32 v[90:91], v[74:75], v[80:81], v[90:91] op_sel:[1,0,0] op_sel_hi:[1,1,1]
	v_mov_b32_dpp v58, v59 quad_perm:[0,1,2,3] row_mask:0xf bank_mask:0xa
	v_pk_fma_f32 v[2:3], v[68:69], v[22:23], v[84:85] op_sel:[0,0,0] op_sel_hi:[0,1,1] neg_lo:[1,0,0] neg_hi:[1,0,0]
	v_pk_fma_f32 v[4:5], v[68:69], v[22:23], v[86:87] op_sel:[1,0,0] op_sel_hi:[1,1,1] neg_lo:[1,0,0] neg_hi:[1,0,0]
	v_pk_fma_f32 v[6:7], v[70:71], v[22:23], v[88:89] op_sel:[0,0,0] op_sel_hi:[0,1,1] neg_lo:[1,0,0] neg_hi:[1,0,0]
	v_pk_fma_f32 v[8:9], v[70:71], v[22:23], v[90:91] op_sel:[1,0,0] op_sel_hi:[1,1,1] neg_lo:[1,0,0] neg_hi:[1,0,0]
	s_waitcnt lgkmcnt(0)
	ds_read_b128 v[60:63], v20 offset:7936
	ds_read_b128 v[64:67], v20 offset:16128
	ds_read_b64 v[80:81], v21 offset:48896
	ds_read_b128 v[72:75], v20 offset:32512
	ds_read_b128 v[68:71], v20 offset:24320
	ds_read_b128 v[76:79], v20 offset:40704
	v_pk_mul_f32 v[22:23], v[2:3], v[36:37] op_sel:[0,0] op_sel_hi:[1,0]
	v_pk_mul_f32 v[26:27], v[2:3], v[92:93] op_sel:[0,0] op_sel_hi:[1,0]
	v_pk_mul_f32 v[84:85], v[2:3], v[40:41] op_sel:[0,0] op_sel_hi:[1,0]
	v_pk_fma_f32 v[22:23], v[4:5], v[36:37], v[22:23] op_sel:[0,1,0] op_sel_hi:[1,1,1]
	v_pk_fma_f32 v[26:27], v[4:5], v[92:93], v[26:27] op_sel:[0,1,0] op_sel_hi:[1,1,1]
	v_pk_mul_f32 v[86:87], v[4:5], v[40:41] op_sel:[0,1] op_sel_hi:[1,1]
	v_pk_fma_f32 v[22:23], v[6:7], v[38:39], v[22:23] op_sel:[0,0,0] op_sel_hi:[1,0,1]
	v_pk_fma_f32 v[26:27], v[6:7], v[94:95], v[26:27] op_sel:[0,0,0] op_sel_hi:[1,0,1]
	v_pk_mul_f32 v[88:89], v[6:7], v[42:43] op_sel:[0,0] op_sel_hi:[1,0]
	v_pk_fma_f32 v[22:23], v[8:9], v[38:39], v[22:23] op_sel:[0,1,0] op_sel_hi:[1,1,1]
	v_pk_fma_f32 v[26:27], v[8:9], v[94:95], v[26:27] op_sel:[0,1,0] op_sel_hi:[1,1,1]
	v_pk_mul_f32 v[90:91], v[8:9], v[42:43] op_sel:[0,1] op_sel_hi:[1,1]
	v_add_f32_dpp v28, v28, v28 row_ror:8 row_mask:0xf bank_mask:0x3
	v_add_f32_dpp v58, v58, v58 row_ror:8 row_mask:0xf bank_mask:0xc
	v_add_f32_dpp v22, v22, v22 quad_perm:[1,0,3,2] row_mask:0xf bank_mask:0xf
	v_add_f32_dpp v23, v23, v23 quad_perm:[1,0,3,2] row_mask:0xf bank_mask:0xf
	v_pk_fma_f32 v[84:85], v[48:49], v[56:57], v[84:85] op_sel:[0,0,0] op_sel_hi:[0,1,1]
	v_mov_b32_dpp v28, v58 quad_perm:[0,1,2,3] row_mask:0xf bank_mask:0xc
	v_add_f32_dpp v22, v22, v22 quad_perm:[2,3,0,1] row_mask:0xf bank_mask:0xf
	v_add_f32_dpp v23, v23, v23 quad_perm:[2,3,0,1] row_mask:0xf bank_mask:0xf
	v_pk_fma_f32 v[86:87], v[48:49], v[56:57], v[86:87] op_sel:[1,0,0] op_sel_hi:[1,1,1]
	v_add_f32_dpp v28, v28, v28 quad_perm:[1,0,3,2] row_mask:0xf bank_mask:0xf
	v_add_f32_dpp v22, v22, v22 row_half_mirror row_mask:0xf bank_mask:0xf
	v_add_f32_dpp v23, v23, v23 row_half_mirror row_mask:0xf bank_mask:0xf
	v_pk_fma_f32 v[88:89], v[50:51], v[56:57], v[88:89] op_sel:[0,0,0] op_sel_hi:[0,1,1]
	v_add_f32_dpp v28, v28, v28 quad_perm:[2,3,0,1] row_mask:0xf bank_mask:0xf
	v_add_f32_dpp v22, v22, v22 row_mirror row_mask:0xf bank_mask:0xf
	v_add_f32_dpp v23, v23, v23 row_mirror row_mask:0xf bank_mask:0xf
	v_pk_fma_f32 v[90:91], v[50:51], v[56:57], v[90:91] op_sel:[1,0,0] op_sel_hi:[1,1,1]
	v_cndmask_b32_e64 v33, v33, v28, s[6:7]
	v_pk_fma_f32 v[2:3], v[44:45], v[22:23], v[84:85] op_sel:[0,0,0] op_sel_hi:[0,1,1] neg_lo:[1,0,0] neg_hi:[1,0,0]
	v_pk_fma_f32 v[4:5], v[44:45], v[22:23], v[86:87] op_sel:[1,0,0] op_sel_hi:[1,1,1] neg_lo:[1,0,0] neg_hi:[1,0,0]
	v_pk_fma_f32 v[6:7], v[46:47], v[22:23], v[88:89] op_sel:[0,0,0] op_sel_hi:[0,1,1] neg_lo:[1,0,0] neg_hi:[1,0,0]
	v_pk_fma_f32 v[8:9], v[46:47], v[22:23], v[90:91] op_sel:[1,0,0] op_sel_hi:[1,1,1] neg_lo:[1,0,0] neg_hi:[1,0,0]
	s_waitcnt lgkmcnt(0)
	v_pk_mul_f32 v[22:23], v[2:3], v[60:61] op_sel:[0,0] op_sel_hi:[1,0]
	v_pk_mul_f32 v[28:29], v[2:3], v[52:53] op_sel:[0,0] op_sel_hi:[1,0]
	v_pk_mul_f32 v[84:85], v[2:3], v[64:65] op_sel:[0,0] op_sel_hi:[1,0]
	v_pk_fma_f32 v[22:23], v[4:5], v[60:61], v[22:23] op_sel:[0,1,0] op_sel_hi:[1,1,1]
	v_pk_fma_f32 v[28:29], v[4:5], v[52:53], v[28:29] op_sel:[0,1,0] op_sel_hi:[1,1,1]
	v_pk_mul_f32 v[86:87], v[4:5], v[64:65] op_sel:[0,1] op_sel_hi:[1,1]
	v_pk_fma_f32 v[22:23], v[6:7], v[62:63], v[22:23] op_sel:[0,0,0] op_sel_hi:[1,0,1]
	v_pk_fma_f32 v[28:29], v[6:7], v[54:55], v[28:29] op_sel:[0,0,0] op_sel_hi:[1,0,1]
	v_pk_mul_f32 v[88:89], v[6:7], v[66:67] op_sel:[0,0] op_sel_hi:[1,0]
	v_pk_fma_f32 v[22:23], v[8:9], v[62:63], v[22:23] op_sel:[0,1,0] op_sel_hi:[1,1,1]
	v_pk_fma_f32 v[28:29], v[8:9], v[54:55], v[28:29] op_sel:[0,1,0] op_sel_hi:[1,1,1]
	v_pk_mul_f32 v[90:91], v[8:9], v[66:67] op_sel:[0,1] op_sel_hi:[1,1]
	v_add_f32_dpp v24, v24, v24 row_ror:12 row_mask:0xf bank_mask:0x5
	v_add_f32_dpp v25, v25, v25 row_ror:4 row_mask:0xf bank_mask:0xa
	v_add_f32_dpp v22, v22, v22 quad_perm:[1,0,3,2] row_mask:0xf bank_mask:0xf
	v_add_f32_dpp v23, v23, v23 quad_perm:[1,0,3,2] row_mask:0xf bank_mask:0xf
	v_pk_fma_f32 v[84:85], v[72:73], v[80:81], v[84:85] op_sel:[0,0,0] op_sel_hi:[0,1,1]
	v_add_f32_dpp v26, v26, v26 row_ror:12 row_mask:0xf bank_mask:0x5
	v_add_f32_dpp v22, v22, v22 quad_perm:[2,3,0,1] row_mask:0xf bank_mask:0xf
	v_add_f32_dpp v23, v23, v23 quad_perm:[2,3,0,1] row_mask:0xf bank_mask:0xf
	v_pk_fma_f32 v[86:87], v[72:73], v[80:81], v[86:87] op_sel:[1,0,0] op_sel_hi:[1,1,1]
	v_add_f32_dpp v27, v27, v27 row_ror:4 row_mask:0xf bank_mask:0xa
	v_add_f32_dpp v22, v22, v22 row_half_mirror row_mask:0xf bank_mask:0xf
	v_add_f32_dpp v23, v23, v23 row_half_mirror row_mask:0xf bank_mask:0xf
	v_pk_fma_f32 v[88:89], v[74:75], v[80:81], v[88:89] op_sel:[0,0,0] op_sel_hi:[0,1,1]
	v_mov_b32_dpp v24, v25 quad_perm:[0,1,2,3] row_mask:0xf bank_mask:0xa
	v_add_f32_dpp v22, v22, v22 row_mirror row_mask:0xf bank_mask:0xf
	v_add_f32_dpp v23, v23, v23 row_mirror row_mask:0xf bank_mask:0xf
	v_pk_fma_f32 v[90:91], v[74:75], v[80:81], v[90:91] op_sel:[1,0,0] op_sel_hi:[1,1,1]
	v_mov_b32_dpp v26, v27 quad_perm:[0,1,2,3] row_mask:0xf bank_mask:0xa
	v_pk_fma_f32 v[2:3], v[68:69], v[22:23], v[84:85] op_sel:[0,0,0] op_sel_hi:[0,1,1] neg_lo:[1,0,0] neg_hi:[1,0,0]
	v_pk_fma_f32 v[4:5], v[68:69], v[22:23], v[86:87] op_sel:[1,0,0] op_sel_hi:[1,1,1] neg_lo:[1,0,0] neg_hi:[1,0,0]
	v_pk_fma_f32 v[6:7], v[70:71], v[22:23], v[88:89] op_sel:[0,0,0] op_sel_hi:[0,1,1] neg_lo:[1,0,0] neg_hi:[1,0,0]
	v_pk_fma_f32 v[8:9], v[70:71], v[22:23], v[90:91] op_sel:[1,0,0] op_sel_hi:[1,1,1] neg_lo:[1,0,0] neg_hi:[1,0,0]
	s_waitcnt lgkmcnt(0)
	v_pk_mul_f32 v[58:59], v[2:3], v[76:77] op_sel:[0,0] op_sel_hi:[1,0]
	v_pk_fma_f32 v[58:59], v[4:5], v[76:77], v[58:59] op_sel:[0,1,0] op_sel_hi:[1,1,1]
	v_pk_fma_f32 v[58:59], v[6:7], v[78:79], v[58:59] op_sel:[0,0,0] op_sel_hi:[1,0,1]
	v_pk_fma_f32 v[58:59], v[8:9], v[78:79], v[58:59] op_sel:[0,1,0] op_sel_hi:[1,1,1]
	v_add_f32_dpp v28, v28, v28 row_ror:12 row_mask:0xf bank_mask:0x5
	v_add_f32_dpp v29, v29, v29 row_ror:4 row_mask:0xf bank_mask:0xa
	v_add_f32_dpp v24, v24, v24 row_ror:8 row_mask:0xf bank_mask:0x3
	v_add_f32_dpp v26, v26, v26 row_ror:8 row_mask:0xf bank_mask:0xc
	v_add_f32_dpp v58, v58, v58 row_ror:12 row_mask:0xf bank_mask:0x5
	v_add_f32_dpp v59, v59, v59 row_ror:4 row_mask:0xf bank_mask:0xa
	v_mov_b32_dpp v24, v26 quad_perm:[0,1,2,3] row_mask:0xf bank_mask:0xc
	v_mov_b32_dpp v28, v29 quad_perm:[0,1,2,3] row_mask:0xf bank_mask:0xa
	v_mov_b32_dpp v58, v59 quad_perm:[0,1,2,3] row_mask:0xf bank_mask:0xa
	v_add_f32_dpp v24, v24, v24 quad_perm:[1,0,3,2] row_mask:0xf bank_mask:0xf
	v_add_f32_dpp v28, v28, v28 row_ror:8 row_mask:0xf bank_mask:0x3
	v_add_f32_dpp v58, v58, v58 row_ror:8 row_mask:0xf bank_mask:0xc
	v_add_f32_dpp v24, v24, v24 quad_perm:[2,3,0,1] row_mask:0xf bank_mask:0xf
	s_nop 0
	v_mov_b32_dpp v28, v58 quad_perm:[0,1,2,3] row_mask:0xf bank_mask:0xc
	v_cndmask_b32_e64 v33, v33, v24, s[8:9]
	s_nop 0
	v_add_f32_dpp v28, v28, v28 quad_perm:[1,0,3,2] row_mask:0xf bank_mask:0xf
	s_nop 1
	v_add_f32_dpp v28, v28, v28 quad_perm:[2,3,0,1] row_mask:0xf bank_mask:0xf
	v_cndmask_b32_e64 v33, v33, v28, s[10:11]
	v_lshl_add_u32 v35, s23, 12, v11
	s_add_i32 s22, s22, 1
	ds_write2st64_b32 v35, v30, v31 offset1:4
	ds_write2st64_b32 v35, v32, v33 offset0:8 offset1:12
	s_cmp_eq_u32 s22, 64
	s_waitcnt lgkmcnt(0)
	s_barrier
	s_cbranch_scc0 .LBB0_1750
	s_setprio 0
	s_lshl_b32 s0, s18, 4
	s_or_b32 s0, s0, s26
	s_ashr_i32 s1, s0, 31
	s_lshl_b64 s[0:1], s[0:1], 6
	s_lshl_b32 s2, s27, 5
	s_or_b32 s0, s0, s2
	v_or_b32_e32 v12, s0, v1
	v_mov_b32_e32 v13, s1
	v_lshlrev_b64 v[12:13], 8, v[12:13]
	v_lshl_add_u64 v[12:13], s[82:83], 0, v[12:13]
	v_mov_b32_e32 v11, 0
	v_lshl_add_u64 v[10:11], v[12:13], 0, v[10:11]
	s_mov_b64 s[0:1], 0x4100000
	v_lshl_add_u64 v[12:13], v[10:11], 0, s[0:1]
	v_add_co_u32_e32 v10, vcc, 0x4100000, v10
	s_nop 1
	v_addc_co_u32_e32 v11, vcc, 0, v11, vcc
	v_mov_b32_e32 v14, v2
	v_mov_b32_e32 v15, v4
	v_mov_b32_e32 v16, v6
	v_mov_b32_e32 v17, v8
	v_mov_b32_e32 v18, v3
	v_mov_b32_e32 v19, v5
	v_mov_b32_e32 v20, v7
	v_mov_b32_e32 v21, v9
	global_store_dwordx4 v[10:11], v[14:17], off
	global_store_dwordx4 v[12:13], v[18:21], off offset:256
